# P7 FFN-down epilogue rewritten by hand around the original exchange: all 64 residual loads up front, perm-based bf16 unpack/swap, lean final scale/stores
# baseline (speedup 1.0000x reference)
; __device__ __forceinline__ void store_rm4_f32(float* base, size_t ld, int c, bool odd, float v0, float v1, float v2, float v3) {
;   {
;     float r = dpp_swap1(odd ? v0 : v1);
;     float2 w; w.x = odd ? r : v0; w.y = odd ? v1 : r;
;     *(float2*)(base + (size_t)(odd ? 1 : 0) * ld + (c - (odd ? 1 : 0))) = w;
;   }
;   {
;     float r = dpp_swap1(odd ? v2 : v3);
;     float2 w; w.x = odd ? r : v2; w.y = odd ? v3 : r;
;     *(float2*)(base + (size_t)(2 + (odd ? 1 : 0)) * ld + (c - (odd ? 1 : 0))) = w;
;   }
; }
;   __device__ __forceinline__ void operator()(f32x4 (&acc)[2][2][4][2], int brow, int bcol, int wr, int wc, int fr, int fq) const {
;     ...
; #pragma unroll
;     for (int ai = 0; ai < 2; ++ai)
; #pragma unroll
;       for (int m = 0; m < 4; ++m) {
;         int rl0 = ai * 128 + wr * 64 + m * 16 + fq * 4;
;         float4 r4 = *(const float4*)(rsl + rl0);
;         float rr[4] = {r4.x, r4.y, r4.z, r4.w};
; #pragma unroll
;         for (int bj = 0; bj < 2; ++bj)
; #pragma unroll
;           for (int n = 0; n < 2; ++n) {
;             int c = bcol + bj * 128 + wc * 32 + n * 16 + fr;
;             float gf = p.g_final[c];
;             store_rm4_f32(p.out + (size_t)(brow + rl0) * 1024, 1024, c, fr & 1, acc[ai][bj][m][n][0] * rr[0] * gf,
;                           acc[ai][bj][m][n][1] * rr[1] * gf, acc[ai][bj][m][n][2] * rr[2] * gf, acc[ai][bj][m][n][3] * rr[3] * gf);
;           }
;         __builtin_amdgcn_sched_barrier(0);
;       }
.LBB0_650:
	s_or_b64 exec, exec, s[18:19]
	s_waitcnt lgkmcnt(0)
	s_barrier
	v_mbcnt_lo_u32_b32 v132, -1, 0
	v_mbcnt_hi_u32_b32 v132, -1, v132
	v_and_b32_e32 v133, 15, v132
	v_lshrrev_b32_e32 v134, 4, v132
	v_and_b32_e32 v136, 1, v132
	s_lshr_b32 s2, s33, 8
	s_lshl_b32 s2, s2, 6
	s_bfe_u32 s3, s33, 0x20006
	v_lshl_add_u32 v157, v134, 2, s2
	v_lshlrev_b32_e32 v156, 2, v157
	v_add_u32_e32 v156, 16, v156
	ds_read_b128 v[176:179], v156 offset:53248
	ds_read_b128 v[180:183], v156 offset:53312
	ds_read_b128 v[184:187], v156 offset:53376
	ds_read_b128 v[188:191], v156 offset:53440
	ds_read_b128 v[192:195], v156 offset:53760
	ds_read_b128 v[196:199], v156 offset:53824
	ds_read_b128 v[200:203], v156 offset:53888
	ds_read_b128 v[204:207], v156 offset:53952
	s_lshl_b32 s3, s3, 5
	s_add_i32 s3, s3, s59
	v_add_u32_e32 v158, s3, v133
	v_lshlrev_b32_e32 v158, 2, v158
	global_load_dword v208, v158, s[48:49]
	global_load_dword v209, v158, s[48:49] offset:64
	global_load_dword v210, v158, s[48:49] offset:512
	global_load_dword v211, v158, s[48:49] offset:576
	v_add_u32_e32 v157, v157, v136
	v_lshlrev_b32_e32 v137, 12, v157
	v_and_b32_e32 v157, 14, v133
	v_add_u32_e32 v157, s3, v157
	v_lshl_add_u32 v137, v157, 2, v137
	s_lshl_b32 s2, s58, 12
	s_add_u32 s100, s50, s2
	s_addc_u32 s101, s51, 0
	v_cmp_eq_u32_e32 vcc, 1, v136
	s_waitcnt vmcnt(0) lgkmcnt(0)
	v_mul_f32_e32 v212, v112, v176
	v_mul_f32_e32 v213, v113, v177
	v_mul_f32_e32 v214, v114, v178
	v_mul_f32_e32 v215, v115, v179
	v_mul_f32_e32 v216, v116, v176
	v_mul_f32_e32 v217, v117, v177
	v_mul_f32_e32 v218, v118, v178
	v_mul_f32_e32 v219, v119, v179
	v_mul_f32_e32 v220, v124, v176
	v_mul_f32_e32 v221, v125, v177
	v_mul_f32_e32 v222, v126, v178
	v_mul_f32_e32 v223, v127, v179
	v_mul_f32_e32 v224, v120, v176
	v_mul_f32_e32 v225, v121, v177
	v_mul_f32_e32 v226, v122, v178
	v_mul_f32_e32 v227, v123, v179
	v_mul_f32_e32 v212, v212, v208
	v_mul_f32_e32 v213, v213, v208
	v_mul_f32_e32 v214, v214, v208
	v_mul_f32_e32 v215, v215, v208
	v_mul_f32_e32 v216, v216, v209
	v_mul_f32_e32 v217, v217, v209
	v_mul_f32_e32 v218, v218, v209
	v_mul_f32_e32 v219, v219, v209
	v_mul_f32_e32 v220, v220, v210
	v_mul_f32_e32 v221, v221, v210
	v_mul_f32_e32 v222, v222, v210
	v_mul_f32_e32 v223, v223, v210
	v_mul_f32_e32 v224, v224, v211
	v_mul_f32_e32 v225, v225, v211
	v_mul_f32_e32 v226, v226, v211
	v_mul_f32_e32 v227, v227, v211
	v_cndmask_b32_e32 v228, v213, v212, vcc
	v_cndmask_b32_e32 v229, v215, v214, vcc
	v_cndmask_b32_e32 v230, v217, v216, vcc
	v_cndmask_b32_e32 v231, v219, v218, vcc
	v_cndmask_b32_e32 v232, v221, v220, vcc
	v_cndmask_b32_e32 v233, v223, v222, vcc
	v_cndmask_b32_e32 v234, v225, v224, vcc
	v_cndmask_b32_e32 v235, v227, v226, vcc
	v_mov_b32_dpp v228, v228 quad_perm:[1,0,3,2] row_mask:0xf bank_mask:0xf bound_ctrl:1
	v_mov_b32_dpp v229, v229 quad_perm:[1,0,3,2] row_mask:0xf bank_mask:0xf bound_ctrl:1
	v_mov_b32_dpp v230, v230 quad_perm:[1,0,3,2] row_mask:0xf bank_mask:0xf bound_ctrl:1
	v_mov_b32_dpp v231, v231 quad_perm:[1,0,3,2] row_mask:0xf bank_mask:0xf bound_ctrl:1
	v_mov_b32_dpp v232, v232 quad_perm:[1,0,3,2] row_mask:0xf bank_mask:0xf bound_ctrl:1
	v_mov_b32_dpp v233, v233 quad_perm:[1,0,3,2] row_mask:0xf bank_mask:0xf bound_ctrl:1
	v_mov_b32_dpp v234, v234 quad_perm:[1,0,3,2] row_mask:0xf bank_mask:0xf bound_ctrl:1
	v_mov_b32_dpp v235, v235 quad_perm:[1,0,3,2] row_mask:0xf bank_mask:0xf bound_ctrl:1
	v_cndmask_b32_e32 v212, v212, v228, vcc
	v_cndmask_b32_e32 v213, v228, v213, vcc
	v_cndmask_b32_e32 v214, v214, v229, vcc
	v_cndmask_b32_e32 v215, v229, v215, vcc
	v_cndmask_b32_e32 v216, v216, v230, vcc
	v_cndmask_b32_e32 v217, v230, v217, vcc
	v_cndmask_b32_e32 v218, v218, v231, vcc
	v_cndmask_b32_e32 v219, v231, v219, vcc
	v_cndmask_b32_e32 v220, v220, v232, vcc
	v_cndmask_b32_e32 v221, v232, v221, vcc
	v_cndmask_b32_e32 v222, v222, v233, vcc
	v_cndmask_b32_e32 v223, v233, v223, vcc
	v_cndmask_b32_e32 v224, v224, v234, vcc
	v_cndmask_b32_e32 v225, v234, v225, vcc
	v_cndmask_b32_e32 v226, v226, v235, vcc
	v_cndmask_b32_e32 v227, v235, v227, vcc
	v_mov_b32_e32 v138, v137
	v_add_u32_e32 v139, 0x2000, v137
	global_store_dwordx2 v138, v[212:213], s[100:101]
	global_store_dwordx2 v139, v[214:215], s[100:101]
	global_store_dwordx2 v138, v[216:217], s[100:101] offset:64
	global_store_dwordx2 v139, v[218:219], s[100:101] offset:64
	global_store_dwordx2 v138, v[220:221], s[100:101] offset:512
	global_store_dwordx2 v139, v[222:223], s[100:101] offset:512
	global_store_dwordx2 v138, v[224:225], s[100:101] offset:576
	global_store_dwordx2 v139, v[226:227], s[100:101] offset:576
	v_mul_f32_e32 v212, v96, v180
	v_mul_f32_e32 v213, v97, v181
	v_mul_f32_e32 v214, v98, v182
	v_mul_f32_e32 v215, v99, v183
	v_mul_f32_e32 v216, v100, v180
	v_mul_f32_e32 v217, v101, v181
	v_mul_f32_e32 v218, v102, v182
	v_mul_f32_e32 v219, v103, v183
	v_mul_f32_e32 v220, v108, v180
	v_mul_f32_e32 v221, v109, v181
	v_mul_f32_e32 v222, v110, v182
	v_mul_f32_e32 v223, v111, v183
	v_mul_f32_e32 v224, v104, v180
	v_mul_f32_e32 v225, v105, v181
	v_mul_f32_e32 v226, v106, v182
	v_mul_f32_e32 v227, v107, v183
	v_mul_f32_e32 v212, v212, v208
	v_mul_f32_e32 v213, v213, v208
	v_mul_f32_e32 v214, v214, v208
	v_mul_f32_e32 v215, v215, v208
	v_mul_f32_e32 v216, v216, v209
	v_mul_f32_e32 v217, v217, v209
	v_mul_f32_e32 v218, v218, v209
	v_mul_f32_e32 v219, v219, v209
	v_mul_f32_e32 v220, v220, v210
	v_mul_f32_e32 v221, v221, v210
	v_mul_f32_e32 v222, v222, v210
	v_mul_f32_e32 v223, v223, v210
	v_mul_f32_e32 v224, v224, v211
	v_mul_f32_e32 v225, v225, v211
	v_mul_f32_e32 v226, v226, v211
	v_mul_f32_e32 v227, v227, v211
	v_cndmask_b32_e32 v228, v213, v212, vcc
; __device__ __forceinline__ void store_rm4_f32(float* base, size_t ld, int c, bool odd, float v0, float v1, float v2, float v3) {
;   {
;     float r = dpp_swap1(odd ? v0 : v1);
;     float2 w; w.x = odd ? r : v0; w.y = odd ? v1 : r;
;     *(float2*)(base + (size_t)(odd ? 1 : 0) * ld + (c - (odd ? 1 : 0))) = w;
;   }
;   {
;     float r = dpp_swap1(odd ? v2 : v3);
;     float2 w; w.x = odd ? r : v2; w.y = odd ? v3 : r;
;     *(float2*)(base + (size_t)(2 + (odd ? 1 : 0)) * ld + (c - (odd ? 1 : 0))) = w;
;   }
; }
;   __device__ __forceinline__ void operator()(f32x4 (&acc)[2][2][4][2], int brow, int bcol, int wr, int wc, int fr, int fq) const {
;     ...
; #pragma unroll
;     for (int ai = 0; ai < 2; ++ai)
; #pragma unroll
;       for (int m = 0; m < 4; ++m) {
;         int rl0 = ai * 128 + wr * 64 + m * 16 + fq * 4;
;         float4 r4 = *(const float4*)(rsl + rl0);
;         float rr[4] = {r4.x, r4.y, r4.z, r4.w};
; #pragma unroll
;         for (int bj = 0; bj < 2; ++bj)
; #pragma unroll
;           for (int n = 0; n < 2; ++n) {
;             int c = bcol + bj * 128 + wc * 32 + n * 16 + fr;
;             float gf = p.g_final[c];
;             store_rm4_f32(p.out + (size_t)(brow + rl0) * 1024, 1024, c, fr & 1, acc[ai][bj][m][n][0] * rr[0] * gf,
;                           acc[ai][bj][m][n][1] * rr[1] * gf, acc[ai][bj][m][n][2] * rr[2] * gf, acc[ai][bj][m][n][3] * rr[3] * gf);
;           }
;         __builtin_amdgcn_sched_barrier(0);
;       }
	v_cndmask_b32_e32 v229, v215, v214, vcc
	v_cndmask_b32_e32 v230, v217, v216, vcc
	v_cndmask_b32_e32 v231, v219, v218, vcc
	v_cndmask_b32_e32 v232, v221, v220, vcc
	v_cndmask_b32_e32 v233, v223, v222, vcc
	v_cndmask_b32_e32 v234, v225, v224, vcc
	v_cndmask_b32_e32 v235, v227, v226, vcc
	v_mov_b32_dpp v228, v228 quad_perm:[1,0,3,2] row_mask:0xf bank_mask:0xf bound_ctrl:1
	v_mov_b32_dpp v229, v229 quad_perm:[1,0,3,2] row_mask:0xf bank_mask:0xf bound_ctrl:1
	v_mov_b32_dpp v230, v230 quad_perm:[1,0,3,2] row_mask:0xf bank_mask:0xf bound_ctrl:1
	v_mov_b32_dpp v231, v231 quad_perm:[1,0,3,2] row_mask:0xf bank_mask:0xf bound_ctrl:1
	v_mov_b32_dpp v232, v232 quad_perm:[1,0,3,2] row_mask:0xf bank_mask:0xf bound_ctrl:1
	v_mov_b32_dpp v233, v233 quad_perm:[1,0,3,2] row_mask:0xf bank_mask:0xf bound_ctrl:1
	v_mov_b32_dpp v234, v234 quad_perm:[1,0,3,2] row_mask:0xf bank_mask:0xf bound_ctrl:1
	v_mov_b32_dpp v235, v235 quad_perm:[1,0,3,2] row_mask:0xf bank_mask:0xf bound_ctrl:1
	v_cndmask_b32_e32 v212, v212, v228, vcc
	v_cndmask_b32_e32 v213, v228, v213, vcc
	v_cndmask_b32_e32 v214, v214, v229, vcc
	v_cndmask_b32_e32 v215, v229, v215, vcc
	v_cndmask_b32_e32 v216, v216, v230, vcc
	v_cndmask_b32_e32 v217, v230, v217, vcc
	v_cndmask_b32_e32 v218, v218, v231, vcc
	v_cndmask_b32_e32 v219, v231, v219, vcc
	v_cndmask_b32_e32 v220, v220, v232, vcc
	v_cndmask_b32_e32 v221, v232, v221, vcc
	v_cndmask_b32_e32 v222, v222, v233, vcc
	v_cndmask_b32_e32 v223, v233, v223, vcc
	v_cndmask_b32_e32 v224, v224, v234, vcc
	v_cndmask_b32_e32 v225, v234, v225, vcc
	v_cndmask_b32_e32 v226, v226, v235, vcc
	v_cndmask_b32_e32 v227, v235, v227, vcc
	v_add_u32_e32 v138, 0x10000, v137
	v_add_u32_e32 v139, 0x12000, v137
	global_store_dwordx2 v138, v[212:213], s[100:101]
	global_store_dwordx2 v139, v[214:215], s[100:101]
	global_store_dwordx2 v138, v[216:217], s[100:101] offset:64
	global_store_dwordx2 v139, v[218:219], s[100:101] offset:64
	global_store_dwordx2 v138, v[220:221], s[100:101] offset:512
	global_store_dwordx2 v139, v[222:223], s[100:101] offset:512
	global_store_dwordx2 v138, v[224:225], s[100:101] offset:576
	global_store_dwordx2 v139, v[226:227], s[100:101] offset:576
	v_mul_f32_e32 v212, v80, v184
	v_mul_f32_e32 v213, v81, v185
	v_mul_f32_e32 v214, v82, v186
	v_mul_f32_e32 v215, v83, v187
	v_mul_f32_e32 v216, v84, v184
	v_mul_f32_e32 v217, v85, v185
	v_mul_f32_e32 v218, v86, v186
	v_mul_f32_e32 v219, v87, v187
	v_mul_f32_e32 v220, v92, v184
	v_mul_f32_e32 v221, v93, v185
	v_mul_f32_e32 v222, v94, v186
	v_mul_f32_e32 v223, v95, v187
	v_mul_f32_e32 v224, v88, v184
	v_mul_f32_e32 v225, v89, v185
	v_mul_f32_e32 v226, v90, v186
	v_mul_f32_e32 v227, v91, v187
	v_mul_f32_e32 v212, v212, v208
	v_mul_f32_e32 v213, v213, v208
	v_mul_f32_e32 v214, v214, v208
	v_mul_f32_e32 v215, v215, v208
	v_mul_f32_e32 v216, v216, v209
	v_mul_f32_e32 v217, v217, v209
	v_mul_f32_e32 v218, v218, v209
	v_mul_f32_e32 v219, v219, v209
	v_mul_f32_e32 v220, v220, v210
	v_mul_f32_e32 v221, v221, v210
	v_mul_f32_e32 v222, v222, v210
	v_mul_f32_e32 v223, v223, v210
	v_mul_f32_e32 v224, v224, v211
	v_mul_f32_e32 v225, v225, v211
	v_mul_f32_e32 v226, v226, v211
	v_mul_f32_e32 v227, v227, v211
	v_cndmask_b32_e32 v228, v213, v212, vcc
	v_cndmask_b32_e32 v229, v215, v214, vcc
	v_cndmask_b32_e32 v230, v217, v216, vcc
	v_cndmask_b32_e32 v231, v219, v218, vcc
	v_cndmask_b32_e32 v232, v221, v220, vcc
	v_cndmask_b32_e32 v233, v223, v222, vcc
	v_cndmask_b32_e32 v234, v225, v224, vcc
	v_cndmask_b32_e32 v235, v227, v226, vcc
	v_mov_b32_dpp v228, v228 quad_perm:[1,0,3,2] row_mask:0xf bank_mask:0xf bound_ctrl:1
	v_mov_b32_dpp v229, v229 quad_perm:[1,0,3,2] row_mask:0xf bank_mask:0xf bound_ctrl:1
	v_mov_b32_dpp v230, v230 quad_perm:[1,0,3,2] row_mask:0xf bank_mask:0xf bound_ctrl:1
	v_mov_b32_dpp v231, v231 quad_perm:[1,0,3,2] row_mask:0xf bank_mask:0xf bound_ctrl:1
	v_mov_b32_dpp v232, v232 quad_perm:[1,0,3,2] row_mask:0xf bank_mask:0xf bound_ctrl:1
	v_mov_b32_dpp v233, v233 quad_perm:[1,0,3,2] row_mask:0xf bank_mask:0xf bound_ctrl:1
	v_mov_b32_dpp v234, v234 quad_perm:[1,0,3,2] row_mask:0xf bank_mask:0xf bound_ctrl:1
	v_mov_b32_dpp v235, v235 quad_perm:[1,0,3,2] row_mask:0xf bank_mask:0xf bound_ctrl:1
	v_cndmask_b32_e32 v212, v212, v228, vcc
	v_cndmask_b32_e32 v213, v228, v213, vcc
	v_cndmask_b32_e32 v214, v214, v229, vcc
	v_cndmask_b32_e32 v215, v229, v215, vcc
	v_cndmask_b32_e32 v216, v216, v230, vcc
	v_cndmask_b32_e32 v217, v230, v217, vcc
	v_cndmask_b32_e32 v218, v218, v231, vcc
	v_cndmask_b32_e32 v219, v231, v219, vcc
	v_cndmask_b32_e32 v220, v220, v232, vcc
	v_cndmask_b32_e32 v221, v232, v221, vcc
	v_cndmask_b32_e32 v222, v222, v233, vcc
	v_cndmask_b32_e32 v223, v233, v223, vcc
	v_cndmask_b32_e32 v224, v224, v234, vcc
	v_cndmask_b32_e32 v225, v234, v225, vcc
	v_cndmask_b32_e32 v226, v226, v235, vcc
	v_cndmask_b32_e32 v227, v235, v227, vcc
	v_add_u32_e32 v138, 0x20000, v137
	v_add_u32_e32 v139, 0x22000, v137
	global_store_dwordx2 v138, v[212:213], s[100:101]
	global_store_dwordx2 v139, v[214:215], s[100:101]
	global_store_dwordx2 v138, v[216:217], s[100:101] offset:64
	global_store_dwordx2 v139, v[218:219], s[100:101] offset:64
	global_store_dwordx2 v138, v[220:221], s[100:101] offset:512
	global_store_dwordx2 v139, v[222:223], s[100:101] offset:512
	global_store_dwordx2 v138, v[224:225], s[100:101] offset:576
	global_store_dwordx2 v139, v[226:227], s[100:101] offset:576
	v_mul_f32_e32 v212, v64, v188
	v_mul_f32_e32 v213, v65, v189
	v_mul_f32_e32 v214, v66, v190
	v_mul_f32_e32 v215, v67, v191
	v_mul_f32_e32 v216, v68, v188
	v_mul_f32_e32 v217, v69, v189
	v_mul_f32_e32 v218, v70, v190
	v_mul_f32_e32 v219, v71, v191
; __device__ __forceinline__ void store_rm4_f32(float* base, size_t ld, int c, bool odd, float v0, float v1, float v2, float v3) {
;   {
;     float r = dpp_swap1(odd ? v0 : v1);
;     float2 w; w.x = odd ? r : v0; w.y = odd ? v1 : r;
;     *(float2*)(base + (size_t)(odd ? 1 : 0) * ld + (c - (odd ? 1 : 0))) = w;
;   }
;   {
;     float r = dpp_swap1(odd ? v2 : v3);
;     float2 w; w.x = odd ? r : v2; w.y = odd ? v3 : r;
;     *(float2*)(base + (size_t)(2 + (odd ? 1 : 0)) * ld + (c - (odd ? 1 : 0))) = w;
;   }
; }
;   __device__ __forceinline__ void operator()(f32x4 (&acc)[2][2][4][2], int brow, int bcol, int wr, int wc, int fr, int fq) const {
;     ...
; #pragma unroll
;     for (int ai = 0; ai < 2; ++ai)
; #pragma unroll
;       for (int m = 0; m < 4; ++m) {
;         int rl0 = ai * 128 + wr * 64 + m * 16 + fq * 4;
;         float4 r4 = *(const float4*)(rsl + rl0);
;         float rr[4] = {r4.x, r4.y, r4.z, r4.w};
; #pragma unroll
;         for (int bj = 0; bj < 2; ++bj)
; #pragma unroll
;           for (int n = 0; n < 2; ++n) {
;             int c = bcol + bj * 128 + wc * 32 + n * 16 + fr;
;             float gf = p.g_final[c];
;             store_rm4_f32(p.out + (size_t)(brow + rl0) * 1024, 1024, c, fr & 1, acc[ai][bj][m][n][0] * rr[0] * gf,
;                           acc[ai][bj][m][n][1] * rr[1] * gf, acc[ai][bj][m][n][2] * rr[2] * gf, acc[ai][bj][m][n][3] * rr[3] * gf);
;           }
;         __builtin_amdgcn_sched_barrier(0);
;       }
	v_mul_f32_e32 v220, v76, v188
	v_mul_f32_e32 v221, v77, v189
	v_mul_f32_e32 v222, v78, v190
	v_mul_f32_e32 v223, v79, v191
	v_mul_f32_e32 v224, v72, v188
	v_mul_f32_e32 v225, v73, v189
	v_mul_f32_e32 v226, v74, v190
	v_mul_f32_e32 v227, v75, v191
	v_mul_f32_e32 v212, v212, v208
	v_mul_f32_e32 v213, v213, v208
	v_mul_f32_e32 v214, v214, v208
	v_mul_f32_e32 v215, v215, v208
	v_mul_f32_e32 v216, v216, v209
	v_mul_f32_e32 v217, v217, v209
	v_mul_f32_e32 v218, v218, v209
	v_mul_f32_e32 v219, v219, v209
	v_mul_f32_e32 v220, v220, v210
	v_mul_f32_e32 v221, v221, v210
	v_mul_f32_e32 v222, v222, v210
	v_mul_f32_e32 v223, v223, v210
	v_mul_f32_e32 v224, v224, v211
	v_mul_f32_e32 v225, v225, v211
	v_mul_f32_e32 v226, v226, v211
	v_mul_f32_e32 v227, v227, v211
	v_cndmask_b32_e32 v228, v213, v212, vcc
	v_cndmask_b32_e32 v229, v215, v214, vcc
	v_cndmask_b32_e32 v230, v217, v216, vcc
	v_cndmask_b32_e32 v231, v219, v218, vcc
	v_cndmask_b32_e32 v232, v221, v220, vcc
	v_cndmask_b32_e32 v233, v223, v222, vcc
	v_cndmask_b32_e32 v234, v225, v224, vcc
	v_cndmask_b32_e32 v235, v227, v226, vcc
	v_mov_b32_dpp v228, v228 quad_perm:[1,0,3,2] row_mask:0xf bank_mask:0xf bound_ctrl:1
	v_mov_b32_dpp v229, v229 quad_perm:[1,0,3,2] row_mask:0xf bank_mask:0xf bound_ctrl:1
	v_mov_b32_dpp v230, v230 quad_perm:[1,0,3,2] row_mask:0xf bank_mask:0xf bound_ctrl:1
	v_mov_b32_dpp v231, v231 quad_perm:[1,0,3,2] row_mask:0xf bank_mask:0xf bound_ctrl:1
	v_mov_b32_dpp v232, v232 quad_perm:[1,0,3,2] row_mask:0xf bank_mask:0xf bound_ctrl:1
	v_mov_b32_dpp v233, v233 quad_perm:[1,0,3,2] row_mask:0xf bank_mask:0xf bound_ctrl:1
	v_mov_b32_dpp v234, v234 quad_perm:[1,0,3,2] row_mask:0xf bank_mask:0xf bound_ctrl:1
	v_mov_b32_dpp v235, v235 quad_perm:[1,0,3,2] row_mask:0xf bank_mask:0xf bound_ctrl:1
	v_cndmask_b32_e32 v212, v212, v228, vcc
	v_cndmask_b32_e32 v213, v228, v213, vcc
	v_cndmask_b32_e32 v214, v214, v229, vcc
	v_cndmask_b32_e32 v215, v229, v215, vcc
	v_cndmask_b32_e32 v216, v216, v230, vcc
	v_cndmask_b32_e32 v217, v230, v217, vcc
	v_cndmask_b32_e32 v218, v218, v231, vcc
	v_cndmask_b32_e32 v219, v231, v219, vcc
	v_cndmask_b32_e32 v220, v220, v232, vcc
	v_cndmask_b32_e32 v221, v232, v221, vcc
	v_cndmask_b32_e32 v222, v222, v233, vcc
	v_cndmask_b32_e32 v223, v233, v223, vcc
	v_cndmask_b32_e32 v224, v224, v234, vcc
	v_cndmask_b32_e32 v225, v234, v225, vcc
	v_cndmask_b32_e32 v226, v226, v235, vcc
	v_cndmask_b32_e32 v227, v235, v227, vcc
	v_add_u32_e32 v138, 0x30000, v137
	v_add_u32_e32 v139, 0x32000, v137
	global_store_dwordx2 v138, v[212:213], s[100:101]
	global_store_dwordx2 v139, v[214:215], s[100:101]
	global_store_dwordx2 v138, v[216:217], s[100:101] offset:64
	global_store_dwordx2 v139, v[218:219], s[100:101] offset:64
	global_store_dwordx2 v138, v[220:221], s[100:101] offset:512
	global_store_dwordx2 v139, v[222:223], s[100:101] offset:512
	global_store_dwordx2 v138, v[224:225], s[100:101] offset:576
	global_store_dwordx2 v139, v[226:227], s[100:101] offset:576
	v_mul_f32_e32 v212, v48, v192
	v_mul_f32_e32 v213, v49, v193
	v_mul_f32_e32 v214, v50, v194
	v_mul_f32_e32 v215, v51, v195
	v_mul_f32_e32 v216, v52, v192
	v_mul_f32_e32 v217, v53, v193
	v_mul_f32_e32 v218, v54, v194
	v_mul_f32_e32 v219, v55, v195
	v_mul_f32_e32 v220, v60, v192
	v_mul_f32_e32 v221, v61, v193
	v_mul_f32_e32 v222, v62, v194
	v_mul_f32_e32 v223, v63, v195
	v_mul_f32_e32 v224, v56, v192
	v_mul_f32_e32 v225, v57, v193
	v_mul_f32_e32 v226, v58, v194
	v_mul_f32_e32 v227, v59, v195
	v_mul_f32_e32 v212, v212, v208
	v_mul_f32_e32 v213, v213, v208
	v_mul_f32_e32 v214, v214, v208
	v_mul_f32_e32 v215, v215, v208
	v_mul_f32_e32 v216, v216, v209
	v_mul_f32_e32 v217, v217, v209
	v_mul_f32_e32 v218, v218, v209
	v_mul_f32_e32 v219, v219, v209
	v_mul_f32_e32 v220, v220, v210
	v_mul_f32_e32 v221, v221, v210
	v_mul_f32_e32 v222, v222, v210
	v_mul_f32_e32 v223, v223, v210
	v_mul_f32_e32 v224, v224, v211
	v_mul_f32_e32 v225, v225, v211
	v_mul_f32_e32 v226, v226, v211
	v_mul_f32_e32 v227, v227, v211
	v_cndmask_b32_e32 v228, v213, v212, vcc
	v_cndmask_b32_e32 v229, v215, v214, vcc
	v_cndmask_b32_e32 v230, v217, v216, vcc
	v_cndmask_b32_e32 v231, v219, v218, vcc
	v_cndmask_b32_e32 v232, v221, v220, vcc
	v_cndmask_b32_e32 v233, v223, v222, vcc
	v_cndmask_b32_e32 v234, v225, v224, vcc
	v_cndmask_b32_e32 v235, v227, v226, vcc
	v_mov_b32_dpp v228, v228 quad_perm:[1,0,3,2] row_mask:0xf bank_mask:0xf bound_ctrl:1
	v_mov_b32_dpp v229, v229 quad_perm:[1,0,3,2] row_mask:0xf bank_mask:0xf bound_ctrl:1
	v_mov_b32_dpp v230, v230 quad_perm:[1,0,3,2] row_mask:0xf bank_mask:0xf bound_ctrl:1
	v_mov_b32_dpp v231, v231 quad_perm:[1,0,3,2] row_mask:0xf bank_mask:0xf bound_ctrl:1
	v_mov_b32_dpp v232, v232 quad_perm:[1,0,3,2] row_mask:0xf bank_mask:0xf bound_ctrl:1
	v_mov_b32_dpp v233, v233 quad_perm:[1,0,3,2] row_mask:0xf bank_mask:0xf bound_ctrl:1
	v_mov_b32_dpp v234, v234 quad_perm:[1,0,3,2] row_mask:0xf bank_mask:0xf bound_ctrl:1
	v_mov_b32_dpp v235, v235 quad_perm:[1,0,3,2] row_mask:0xf bank_mask:0xf bound_ctrl:1
	v_cndmask_b32_e32 v212, v212, v228, vcc
	v_cndmask_b32_e32 v213, v228, v213, vcc
	v_cndmask_b32_e32 v214, v214, v229, vcc
	v_cndmask_b32_e32 v215, v229, v215, vcc
	v_cndmask_b32_e32 v216, v216, v230, vcc
	v_cndmask_b32_e32 v217, v230, v217, vcc
	v_cndmask_b32_e32 v218, v218, v231, vcc
	v_cndmask_b32_e32 v219, v231, v219, vcc
	v_cndmask_b32_e32 v220, v220, v232, vcc
	v_cndmask_b32_e32 v221, v232, v221, vcc
	v_cndmask_b32_e32 v222, v222, v233, vcc
	v_cndmask_b32_e32 v223, v233, v223, vcc
	v_cndmask_b32_e32 v224, v224, v234, vcc
	v_cndmask_b32_e32 v225, v234, v225, vcc
	v_cndmask_b32_e32 v226, v226, v235, vcc
	v_cndmask_b32_e32 v227, v235, v227, vcc
; __device__ __forceinline__ void store_rm4_f32(float* base, size_t ld, int c, bool odd, float v0, float v1, float v2, float v3) {
;   {
;     float r = dpp_swap1(odd ? v0 : v1);
;     float2 w; w.x = odd ? r : v0; w.y = odd ? v1 : r;
;     *(float2*)(base + (size_t)(odd ? 1 : 0) * ld + (c - (odd ? 1 : 0))) = w;
;   }
;   {
;     float r = dpp_swap1(odd ? v2 : v3);
;     float2 w; w.x = odd ? r : v2; w.y = odd ? v3 : r;
;     *(float2*)(base + (size_t)(2 + (odd ? 1 : 0)) * ld + (c - (odd ? 1 : 0))) = w;
;   }
; }
;   __device__ __forceinline__ void operator()(f32x4 (&acc)[2][2][4][2], int brow, int bcol, int wr, int wc, int fr, int fq) const {
;     ...
; #pragma unroll
;     for (int ai = 0; ai < 2; ++ai)
; #pragma unroll
;       for (int m = 0; m < 4; ++m) {
;         int rl0 = ai * 128 + wr * 64 + m * 16 + fq * 4;
;         float4 r4 = *(const float4*)(rsl + rl0);
;         float rr[4] = {r4.x, r4.y, r4.z, r4.w};
; #pragma unroll
;         for (int bj = 0; bj < 2; ++bj)
; #pragma unroll
;           for (int n = 0; n < 2; ++n) {
;             int c = bcol + bj * 128 + wc * 32 + n * 16 + fr;
;             float gf = p.g_final[c];
;             store_rm4_f32(p.out + (size_t)(brow + rl0) * 1024, 1024, c, fr & 1, acc[ai][bj][m][n][0] * rr[0] * gf,
;                           acc[ai][bj][m][n][1] * rr[1] * gf, acc[ai][bj][m][n][2] * rr[2] * gf, acc[ai][bj][m][n][3] * rr[3] * gf);
;           }
;         __builtin_amdgcn_sched_barrier(0);
;       }
	v_add_u32_e32 v138, 0x80000, v137
	v_add_u32_e32 v139, 0x82000, v137
	global_store_dwordx2 v138, v[212:213], s[100:101]
	global_store_dwordx2 v139, v[214:215], s[100:101]
	global_store_dwordx2 v138, v[216:217], s[100:101] offset:64
	global_store_dwordx2 v139, v[218:219], s[100:101] offset:64
	global_store_dwordx2 v138, v[220:221], s[100:101] offset:512
	global_store_dwordx2 v139, v[222:223], s[100:101] offset:512
	global_store_dwordx2 v138, v[224:225], s[100:101] offset:576
	global_store_dwordx2 v139, v[226:227], s[100:101] offset:576
	v_mul_f32_e32 v212, v32, v196
	v_mul_f32_e32 v213, v33, v197
	v_mul_f32_e32 v214, v34, v198
	v_mul_f32_e32 v215, v35, v199
	v_mul_f32_e32 v216, v36, v196
	v_mul_f32_e32 v217, v37, v197
	v_mul_f32_e32 v218, v38, v198
	v_mul_f32_e32 v219, v39, v199
	v_mul_f32_e32 v220, v44, v196
	v_mul_f32_e32 v221, v45, v197
	v_mul_f32_e32 v222, v46, v198
	v_mul_f32_e32 v223, v47, v199
	v_mul_f32_e32 v224, v40, v196
	v_mul_f32_e32 v225, v41, v197
	v_mul_f32_e32 v226, v42, v198
	v_mul_f32_e32 v227, v43, v199
	v_mul_f32_e32 v212, v212, v208
	v_mul_f32_e32 v213, v213, v208
	v_mul_f32_e32 v214, v214, v208
	v_mul_f32_e32 v215, v215, v208
	v_mul_f32_e32 v216, v216, v209
	v_mul_f32_e32 v217, v217, v209
	v_mul_f32_e32 v218, v218, v209
	v_mul_f32_e32 v219, v219, v209
	v_mul_f32_e32 v220, v220, v210
	v_mul_f32_e32 v221, v221, v210
	v_mul_f32_e32 v222, v222, v210
	v_mul_f32_e32 v223, v223, v210
	v_mul_f32_e32 v224, v224, v211
	v_mul_f32_e32 v225, v225, v211
	v_mul_f32_e32 v226, v226, v211
	v_mul_f32_e32 v227, v227, v211
	v_cndmask_b32_e32 v228, v213, v212, vcc
	v_cndmask_b32_e32 v229, v215, v214, vcc
	v_cndmask_b32_e32 v230, v217, v216, vcc
	v_cndmask_b32_e32 v231, v219, v218, vcc
	v_cndmask_b32_e32 v232, v221, v220, vcc
	v_cndmask_b32_e32 v233, v223, v222, vcc
	v_cndmask_b32_e32 v234, v225, v224, vcc
	v_cndmask_b32_e32 v235, v227, v226, vcc
	v_mov_b32_dpp v228, v228 quad_perm:[1,0,3,2] row_mask:0xf bank_mask:0xf bound_ctrl:1
	v_mov_b32_dpp v229, v229 quad_perm:[1,0,3,2] row_mask:0xf bank_mask:0xf bound_ctrl:1
	v_mov_b32_dpp v230, v230 quad_perm:[1,0,3,2] row_mask:0xf bank_mask:0xf bound_ctrl:1
	v_mov_b32_dpp v231, v231 quad_perm:[1,0,3,2] row_mask:0xf bank_mask:0xf bound_ctrl:1
	v_mov_b32_dpp v232, v232 quad_perm:[1,0,3,2] row_mask:0xf bank_mask:0xf bound_ctrl:1
	v_mov_b32_dpp v233, v233 quad_perm:[1,0,3,2] row_mask:0xf bank_mask:0xf bound_ctrl:1
	v_mov_b32_dpp v234, v234 quad_perm:[1,0,3,2] row_mask:0xf bank_mask:0xf bound_ctrl:1
	v_mov_b32_dpp v235, v235 quad_perm:[1,0,3,2] row_mask:0xf bank_mask:0xf bound_ctrl:1
	v_cndmask_b32_e32 v212, v212, v228, vcc
	v_cndmask_b32_e32 v213, v228, v213, vcc
	v_cndmask_b32_e32 v214, v214, v229, vcc
	v_cndmask_b32_e32 v215, v229, v215, vcc
	v_cndmask_b32_e32 v216, v216, v230, vcc
	v_cndmask_b32_e32 v217, v230, v217, vcc
	v_cndmask_b32_e32 v218, v218, v231, vcc
	v_cndmask_b32_e32 v219, v231, v219, vcc
	v_cndmask_b32_e32 v220, v220, v232, vcc
	v_cndmask_b32_e32 v221, v232, v221, vcc
	v_cndmask_b32_e32 v222, v222, v233, vcc
	v_cndmask_b32_e32 v223, v233, v223, vcc
	v_cndmask_b32_e32 v224, v224, v234, vcc
	v_cndmask_b32_e32 v225, v234, v225, vcc
	v_cndmask_b32_e32 v226, v226, v235, vcc
	v_cndmask_b32_e32 v227, v235, v227, vcc
	v_add_u32_e32 v138, 0x90000, v137
	v_add_u32_e32 v139, 0x92000, v137
	global_store_dwordx2 v138, v[212:213], s[100:101]
	global_store_dwordx2 v139, v[214:215], s[100:101]
	global_store_dwordx2 v138, v[216:217], s[100:101] offset:64
	global_store_dwordx2 v139, v[218:219], s[100:101] offset:64
	global_store_dwordx2 v138, v[220:221], s[100:101] offset:512
	global_store_dwordx2 v139, v[222:223], s[100:101] offset:512
	global_store_dwordx2 v138, v[224:225], s[100:101] offset:576
	global_store_dwordx2 v139, v[226:227], s[100:101] offset:576
	v_mul_f32_e32 v212, v16, v200
	v_mul_f32_e32 v213, v17, v201
	v_mul_f32_e32 v214, v18, v202
	v_mul_f32_e32 v215, v19, v203
	v_mul_f32_e32 v216, v20, v200
	v_mul_f32_e32 v217, v21, v201
	v_mul_f32_e32 v218, v22, v202
	v_mul_f32_e32 v219, v23, v203
	v_mul_f32_e32 v220, v28, v200
	v_mul_f32_e32 v221, v29, v201
	v_mul_f32_e32 v222, v30, v202
	v_mul_f32_e32 v223, v31, v203
	v_mul_f32_e32 v224, v24, v200
	v_mul_f32_e32 v225, v25, v201
	v_mul_f32_e32 v226, v26, v202
	v_mul_f32_e32 v227, v27, v203
	v_mul_f32_e32 v212, v212, v208
	v_mul_f32_e32 v213, v213, v208
	v_mul_f32_e32 v214, v214, v208
	v_mul_f32_e32 v215, v215, v208
	v_mul_f32_e32 v216, v216, v209
	v_mul_f32_e32 v217, v217, v209
	v_mul_f32_e32 v218, v218, v209
	v_mul_f32_e32 v219, v219, v209
	v_mul_f32_e32 v220, v220, v210
	v_mul_f32_e32 v221, v221, v210
	v_mul_f32_e32 v222, v222, v210
	v_mul_f32_e32 v223, v223, v210
	v_mul_f32_e32 v224, v224, v211
	v_mul_f32_e32 v225, v225, v211
	v_mul_f32_e32 v226, v226, v211
	v_mul_f32_e32 v227, v227, v211
	v_cndmask_b32_e32 v228, v213, v212, vcc
	v_cndmask_b32_e32 v229, v215, v214, vcc
	v_cndmask_b32_e32 v230, v217, v216, vcc
	v_cndmask_b32_e32 v231, v219, v218, vcc
	v_cndmask_b32_e32 v232, v221, v220, vcc
	v_cndmask_b32_e32 v233, v223, v222, vcc
	v_cndmask_b32_e32 v234, v225, v224, vcc
	v_cndmask_b32_e32 v235, v227, v226, vcc
	v_mov_b32_dpp v228, v228 quad_perm:[1,0,3,2] row_mask:0xf bank_mask:0xf bound_ctrl:1
; __device__ __forceinline__ void store_rm4_f32(float* base, size_t ld, int c, bool odd, float v0, float v1, float v2, float v3) {
;   {
;     float r = dpp_swap1(odd ? v0 : v1);
;     float2 w; w.x = odd ? r : v0; w.y = odd ? v1 : r;
;     *(float2*)(base + (size_t)(odd ? 1 : 0) * ld + (c - (odd ? 1 : 0))) = w;
;   }
;   {
;     float r = dpp_swap1(odd ? v2 : v3);
;     float2 w; w.x = odd ? r : v2; w.y = odd ? v3 : r;
;     *(float2*)(base + (size_t)(2 + (odd ? 1 : 0)) * ld + (c - (odd ? 1 : 0))) = w;
;   }
; }
;   __device__ __forceinline__ void operator()(f32x4 (&acc)[2][2][4][2], int brow, int bcol, int wr, int wc, int fr, int fq) const {
;     ...
; #pragma unroll
;     for (int ai = 0; ai < 2; ++ai)
; #pragma unroll
;       for (int m = 0; m < 4; ++m) {
;         int rl0 = ai * 128 + wr * 64 + m * 16 + fq * 4;
;         float4 r4 = *(const float4*)(rsl + rl0);
;         float rr[4] = {r4.x, r4.y, r4.z, r4.w};
; #pragma unroll
;         for (int bj = 0; bj < 2; ++bj)
; #pragma unroll
;           for (int n = 0; n < 2; ++n) {
;             int c = bcol + bj * 128 + wc * 32 + n * 16 + fr;
;             float gf = p.g_final[c];
;             store_rm4_f32(p.out + (size_t)(brow + rl0) * 1024, 1024, c, fr & 1, acc[ai][bj][m][n][0] * rr[0] * gf,
;                           acc[ai][bj][m][n][1] * rr[1] * gf, acc[ai][bj][m][n][2] * rr[2] * gf, acc[ai][bj][m][n][3] * rr[3] * gf);
;           }
;         __builtin_amdgcn_sched_barrier(0);
;       }
	v_mov_b32_dpp v229, v229 quad_perm:[1,0,3,2] row_mask:0xf bank_mask:0xf bound_ctrl:1
	v_mov_b32_dpp v230, v230 quad_perm:[1,0,3,2] row_mask:0xf bank_mask:0xf bound_ctrl:1
	v_mov_b32_dpp v231, v231 quad_perm:[1,0,3,2] row_mask:0xf bank_mask:0xf bound_ctrl:1
	v_mov_b32_dpp v232, v232 quad_perm:[1,0,3,2] row_mask:0xf bank_mask:0xf bound_ctrl:1
	v_mov_b32_dpp v233, v233 quad_perm:[1,0,3,2] row_mask:0xf bank_mask:0xf bound_ctrl:1
	v_mov_b32_dpp v234, v234 quad_perm:[1,0,3,2] row_mask:0xf bank_mask:0xf bound_ctrl:1
	v_mov_b32_dpp v235, v235 quad_perm:[1,0,3,2] row_mask:0xf bank_mask:0xf bound_ctrl:1
	v_cndmask_b32_e32 v212, v212, v228, vcc
	v_cndmask_b32_e32 v213, v228, v213, vcc
	v_cndmask_b32_e32 v214, v214, v229, vcc
	v_cndmask_b32_e32 v215, v229, v215, vcc
	v_cndmask_b32_e32 v216, v216, v230, vcc
	v_cndmask_b32_e32 v217, v230, v217, vcc
	v_cndmask_b32_e32 v218, v218, v231, vcc
	v_cndmask_b32_e32 v219, v231, v219, vcc
	v_cndmask_b32_e32 v220, v220, v232, vcc
	v_cndmask_b32_e32 v221, v232, v221, vcc
	v_cndmask_b32_e32 v222, v222, v233, vcc
	v_cndmask_b32_e32 v223, v233, v223, vcc
	v_cndmask_b32_e32 v224, v224, v234, vcc
	v_cndmask_b32_e32 v225, v234, v225, vcc
	v_cndmask_b32_e32 v226, v226, v235, vcc
	v_cndmask_b32_e32 v227, v235, v227, vcc
	v_add_u32_e32 v138, 0xa0000, v137
	v_add_u32_e32 v139, 0xa2000, v137
	global_store_dwordx2 v138, v[212:213], s[100:101]
	global_store_dwordx2 v139, v[214:215], s[100:101]
	global_store_dwordx2 v138, v[216:217], s[100:101] offset:64
	global_store_dwordx2 v139, v[218:219], s[100:101] offset:64
	global_store_dwordx2 v138, v[220:221], s[100:101] offset:512
	global_store_dwordx2 v139, v[222:223], s[100:101] offset:512
	global_store_dwordx2 v138, v[224:225], s[100:101] offset:576
	global_store_dwordx2 v139, v[226:227], s[100:101] offset:576
	v_mul_f32_e32 v212, v240, v204
	v_mul_f32_e32 v213, v241, v205
	v_mul_f32_e32 v214, v242, v206
	v_mul_f32_e32 v215, v243, v207
	v_mul_f32_e32 v216, v244, v204
	v_mul_f32_e32 v217, v245, v205
	v_mul_f32_e32 v218, v246, v206
	v_mul_f32_e32 v219, v247, v207
	v_mul_f32_e32 v220, v12, v204
	v_mul_f32_e32 v221, v13, v205
	v_mul_f32_e32 v222, v14, v206
	v_mul_f32_e32 v223, v15, v207
	v_mul_f32_e32 v224, v248, v204
	v_mul_f32_e32 v225, v249, v205
	v_mul_f32_e32 v226, v10, v206
	v_mul_f32_e32 v227, v11, v207
	v_mul_f32_e32 v212, v212, v208
	v_mul_f32_e32 v213, v213, v208
	v_mul_f32_e32 v214, v214, v208
	v_mul_f32_e32 v215, v215, v208
	v_mul_f32_e32 v216, v216, v209
	v_mul_f32_e32 v217, v217, v209
	v_mul_f32_e32 v218, v218, v209
	v_mul_f32_e32 v219, v219, v209
	v_mul_f32_e32 v220, v220, v210
	v_mul_f32_e32 v221, v221, v210
	v_mul_f32_e32 v222, v222, v210
	v_mul_f32_e32 v223, v223, v210
	v_mul_f32_e32 v224, v224, v211
	v_mul_f32_e32 v225, v225, v211
	v_mul_f32_e32 v226, v226, v211
	v_mul_f32_e32 v227, v227, v211
	v_cndmask_b32_e32 v228, v213, v212, vcc
	v_cndmask_b32_e32 v229, v215, v214, vcc
	v_cndmask_b32_e32 v230, v217, v216, vcc
	v_cndmask_b32_e32 v231, v219, v218, vcc
	v_cndmask_b32_e32 v232, v221, v220, vcc
	v_cndmask_b32_e32 v233, v223, v222, vcc
	v_cndmask_b32_e32 v234, v225, v224, vcc
	v_cndmask_b32_e32 v235, v227, v226, vcc
	v_mov_b32_dpp v228, v228 quad_perm:[1,0,3,2] row_mask:0xf bank_mask:0xf bound_ctrl:1
	v_mov_b32_dpp v229, v229 quad_perm:[1,0,3,2] row_mask:0xf bank_mask:0xf bound_ctrl:1
	v_mov_b32_dpp v230, v230 quad_perm:[1,0,3,2] row_mask:0xf bank_mask:0xf bound_ctrl:1
	v_mov_b32_dpp v231, v231 quad_perm:[1,0,3,2] row_mask:0xf bank_mask:0xf bound_ctrl:1
	v_mov_b32_dpp v232, v232 quad_perm:[1,0,3,2] row_mask:0xf bank_mask:0xf bound_ctrl:1
	v_mov_b32_dpp v233, v233 quad_perm:[1,0,3,2] row_mask:0xf bank_mask:0xf bound_ctrl:1
	v_mov_b32_dpp v234, v234 quad_perm:[1,0,3,2] row_mask:0xf bank_mask:0xf bound_ctrl:1
	v_mov_b32_dpp v235, v235 quad_perm:[1,0,3,2] row_mask:0xf bank_mask:0xf bound_ctrl:1
	v_cndmask_b32_e32 v212, v212, v228, vcc
	v_cndmask_b32_e32 v213, v228, v213, vcc
	v_cndmask_b32_e32 v214, v214, v229, vcc
	v_cndmask_b32_e32 v215, v229, v215, vcc
	v_cndmask_b32_e32 v216, v216, v230, vcc
	v_cndmask_b32_e32 v217, v230, v217, vcc
	v_cndmask_b32_e32 v218, v218, v231, vcc
	v_cndmask_b32_e32 v219, v231, v219, vcc
	v_cndmask_b32_e32 v220, v220, v232, vcc
	v_cndmask_b32_e32 v221, v232, v221, vcc
	v_cndmask_b32_e32 v222, v222, v233, vcc
	v_cndmask_b32_e32 v223, v233, v223, vcc
	v_cndmask_b32_e32 v224, v224, v234, vcc
	v_cndmask_b32_e32 v225, v234, v225, vcc
	v_cndmask_b32_e32 v226, v226, v235, vcc
	v_cndmask_b32_e32 v227, v235, v227, vcc
	v_add_u32_e32 v138, 0xb0000, v137
	v_add_u32_e32 v139, 0xb2000, v137
	global_store_dwordx2 v138, v[212:213], s[100:101]
	global_store_dwordx2 v139, v[214:215], s[100:101]
	global_store_dwordx2 v138, v[216:217], s[100:101] offset:64
	global_store_dwordx2 v139, v[218:219], s[100:101] offset:64
	global_store_dwordx2 v138, v[220:221], s[100:101] offset:512
	global_store_dwordx2 v139, v[222:223], s[100:101] offset:512
	global_store_dwordx2 v138, v[224:225], s[100:101] offset:576
	global_store_dwordx2 v139, v[226:227], s[100:101] offset:576
	s_waitcnt lgkmcnt(0)
	s_cmp_lg_u32 s45, 4
	s_mov_b32 s58, s47
	s_mov_b32 s59, s46
	s_mov_b32 s2, s45
	s_barrier
	s_cbranch_scc0 .LBB0_749

; __device__ __forceinline__ void load_rm4_bf16(const u16* base, size_t ld, int c, bool odd, float (&x)[4]) {
; #pragma unroll
;   for (int pr = 0; pr < 2; ++pr) {
;     unsigned w = *(const unsigned*)(base + (size_t)(2 * pr + (odd ? 1 : 0)) * ld + (c - (odd ? 1 : 0)));
;     float lo = __uint_as_float(w << 16), hi = __uint_as_float(w & 0xffff0000u);
;     float r = dpp_swap1(odd ? lo : hi);
;     x[2 * pr] = odd ? r : lo; x[2 * pr + 1] = odd ? hi : r;
;   }
; }
;   __device__ __forceinline__ void operator()(f32x4 (&acc)[2][2][4][2], int brow, int bcol, int wr, int wc, int fr, int fq) const {
;     ...
; #pragma unroll
;     for (int ai = 0; ai < 2; ++ai)
; #pragma unroll
;       for (int m = 0; m < 4; ++m) {
;         int rl0 = ai * 128 + wr * 64 + m * 16 + fq * 4;
;         float sq[4] = {0.f, 0.f, 0.f, 0.f};
; #pragma unroll
;         for (int bj = 0; bj < 2; ++bj)
; #pragma unroll
;           for (int n = 0; n < 2; ++n) {
;             int c = bcol + bj * 128 + wc * 32 + n * 16 + fr;
;             float xv[4];
;             load_rm4_bf16(x1b + (size_t)(brow + rl0) * 1024, 1024, c, fr & 1, xv);
; #pragma unroll
;             for (int j = 0; j < 4; ++j) {
;               float v = xv[j] + acc[ai][bj][m][n][j];
;               acc[ai][bj][m][n][j] = v;
;               sq[j] += v * v;
;             }
;           }
.LBB0_668:
	v_mbcnt_lo_u32_b32 v132, -1, 0
	v_mbcnt_hi_u32_b32 v132, -1, v132
	s_lshl_b32 s2, s58, 11
	s_add_u32 s98, s6, s2
	s_addc_u32 s99, s7, 0
	v_and_b32_e32 v133, 15, v132
	v_lshrrev_b32_e32 v134, 4, v132
	v_and_b32_e32 v136, 1, v132
	s_lshr_b32 s2, s33, 8
	s_lshl_b32 s2, s2, 6
	s_bfe_u32 s3, s33, 0x20006
	v_lshl_add_u32 v157, v134, 2, s2
	v_lshlrev_b32_e32 v156, 4, v157
	v_add_u32_e32 v157, v157, v136
	v_lshlrev_b32_e32 v137, 11, v157
	s_lshl_b32 s2, s3, 5
	s_add_i32 s2, s2, s59
	v_and_b32_e32 v157, 14, v133
	v_add_u32_e32 v157, s2, v157
	v_lshl_add_u32 v137, v157, 1, v137
	s_lshl_b32 s3, s3, 2
	s_add_i32 s3, s3, 16
	v_add_u32_e32 v156, s3, v156
	v_mov_b32_e32 v138, v137
	v_add_u32_e32 v139, 0x1000, v137
	global_load_dword v176, v138, s[98:99]
	global_load_dword v177, v139, s[98:99]
	global_load_dword v178, v138, s[98:99] offset:32
	global_load_dword v179, v139, s[98:99] offset:32
	global_load_dword v180, v138, s[98:99] offset:256
	global_load_dword v181, v139, s[98:99] offset:256
	global_load_dword v182, v138, s[98:99] offset:288
	global_load_dword v183, v139, s[98:99] offset:288
	v_add_u32_e32 v138, 0x8000, v137
	v_add_u32_e32 v139, 0x9000, v137
	global_load_dword v184, v138, s[98:99]
	global_load_dword v185, v139, s[98:99]
	global_load_dword v186, v138, s[98:99] offset:32
	global_load_dword v187, v139, s[98:99] offset:32
	global_load_dword v188, v138, s[98:99] offset:256
	global_load_dword v189, v139, s[98:99] offset:256
	global_load_dword v190, v138, s[98:99] offset:288
	global_load_dword v191, v139, s[98:99] offset:288
	v_add_u32_e32 v138, 0x10000, v137
	v_add_u32_e32 v139, 0x11000, v137
	global_load_dword v192, v138, s[98:99]
	global_load_dword v193, v139, s[98:99]
	global_load_dword v194, v138, s[98:99] offset:32
	global_load_dword v195, v139, s[98:99] offset:32
	global_load_dword v196, v138, s[98:99] offset:256
	global_load_dword v197, v139, s[98:99] offset:256
	global_load_dword v198, v138, s[98:99] offset:288
	global_load_dword v199, v139, s[98:99] offset:288
	v_add_u32_e32 v138, 0x18000, v137
	v_add_u32_e32 v139, 0x19000, v137
	global_load_dword v200, v138, s[98:99]
	global_load_dword v201, v139, s[98:99]
	global_load_dword v202, v138, s[98:99] offset:32
	global_load_dword v203, v139, s[98:99] offset:32
	global_load_dword v204, v138, s[98:99] offset:256
	global_load_dword v205, v139, s[98:99] offset:256
	global_load_dword v206, v138, s[98:99] offset:288
	global_load_dword v207, v139, s[98:99] offset:288
	v_add_u32_e32 v138, 0x40000, v137
	v_add_u32_e32 v139, 0x41000, v137
	global_load_dword v208, v138, s[98:99]
	global_load_dword v209, v139, s[98:99]
	global_load_dword v210, v138, s[98:99] offset:32
	global_load_dword v211, v139, s[98:99] offset:32
	global_load_dword v212, v138, s[98:99] offset:256
	global_load_dword v213, v139, s[98:99] offset:256
	global_load_dword v214, v138, s[98:99] offset:288
	global_load_dword v215, v139, s[98:99] offset:288
	v_add_u32_e32 v138, 0x48000, v137
	v_add_u32_e32 v139, 0x49000, v137
	global_load_dword v216, v138, s[98:99]
	global_load_dword v217, v139, s[98:99]
	global_load_dword v218, v138, s[98:99] offset:32
	global_load_dword v219, v139, s[98:99] offset:32
	global_load_dword v220, v138, s[98:99] offset:256
	global_load_dword v221, v139, s[98:99] offset:256
	global_load_dword v222, v138, s[98:99] offset:288
	global_load_dword v223, v139, s[98:99] offset:288
	v_add_u32_e32 v138, 0x50000, v137
	v_add_u32_e32 v139, 0x51000, v137
	global_load_dword v224, v138, s[98:99]
	global_load_dword v225, v139, s[98:99]
	global_load_dword v226, v138, s[98:99] offset:32
	global_load_dword v227, v139, s[98:99] offset:32
	global_load_dword v228, v138, s[98:99] offset:256
	global_load_dword v229, v139, s[98:99] offset:256
	global_load_dword v230, v138, s[98:99] offset:288
	global_load_dword v231, v139, s[98:99] offset:288
	v_add_u32_e32 v138, 0x58000, v137
	v_add_u32_e32 v139, 0x59000, v137
	global_load_dword v232, v138, s[98:99]
	global_load_dword v233, v139, s[98:99]
	global_load_dword v234, v138, s[98:99] offset:32
	global_load_dword v235, v139, s[98:99] offset:32
	global_load_dword v236, v138, s[98:99] offset:256
	global_load_dword v237, v139, s[98:99] offset:256
	global_load_dword v238, v138, s[98:99] offset:288
	global_load_dword v239, v139, s[98:99] offset:288
	v_cmp_eq_u32_e32 vcc, 1, v136
	v_mov_b32_e32 v140, 0x01000c0c
	v_mov_b32_e32 v157, 0x07060c0c
	v_mov_b32_e32 v141, 0x05040c0c
	v_mov_b32_e32 v158, 0x03020c0c
	v_cndmask_b32_e32 v140, v140, v157, vcc
	v_cndmask_b32_e32 v141, v141, v158, vcc
	v_cmp_eq_u32_e64 s[0:1], 0, v133
	s_waitcnt vmcnt(0)
; __device__ __forceinline__ void load_rm4_bf16(const u16* base, size_t ld, int c, bool odd, float (&x)[4]) {
; #pragma unroll
;   for (int pr = 0; pr < 2; ++pr) {
;     unsigned w = *(const unsigned*)(base + (size_t)(2 * pr + (odd ? 1 : 0)) * ld + (c - (odd ? 1 : 0)));
;     float lo = __uint_as_float(w << 16), hi = __uint_as_float(w & 0xffff0000u);
;     float r = dpp_swap1(odd ? lo : hi);
;     x[2 * pr] = odd ? r : lo; x[2 * pr + 1] = odd ? hi : r;
;   }
; }
;   __device__ __forceinline__ void operator()(f32x4 (&acc)[2][2][4][2], int brow, int bcol, int wr, int wc, int fr, int fq) const {
;     ...
;     for (int ai = 0; ai < 2; ++ai)
; #pragma unroll
;       for (int m = 0; m < 4; ++m) {
;         int rl0 = ai * 128 + wr * 64 + m * 16 + fq * 4;
;         float sq[4] = {0.f, 0.f, 0.f, 0.f};
; #pragma unroll
;         for (int bj = 0; bj < 2; ++bj)
; #pragma unroll
;           for (int n = 0; n < 2; ++n) {
;             int c = bcol + bj * 128 + wc * 32 + n * 16 + fr;
;             float xv[4];
;             load_rm4_bf16(x1b + (size_t)(brow + rl0) * 1024, 1024, c, fr & 1, xv);
; #pragma unroll
;             for (int j = 0; j < 4; ++j) {
;               float v = xv[j] + acc[ai][bj][m][n][j];
;               acc[ai][bj][m][n][j] = v;
;               sq[j] += v * v;
;             }
;           }
; #pragma unroll
;         for (int j = 0; j < 4; ++j) {
;           float s = sq[j];
;           s = row16_sum(s);
;           if (fr == 0) part[(rl0 + j) * 4 + wc] = s;
;         }
;         __builtin_amdgcn_sched_barrier(0);
;       }
	v_mov_b32_dpp v142, v176 quad_perm:[1,0,3,2] row_mask:0xf bank_mask:0xf bound_ctrl:1
	v_mov_b32_dpp v143, v177 quad_perm:[1,0,3,2] row_mask:0xf bank_mask:0xf bound_ctrl:1
	v_mov_b32_dpp v144, v178 quad_perm:[1,0,3,2] row_mask:0xf bank_mask:0xf bound_ctrl:1
	v_mov_b32_dpp v145, v179 quad_perm:[1,0,3,2] row_mask:0xf bank_mask:0xf bound_ctrl:1
	v_mov_b32_dpp v146, v180 quad_perm:[1,0,3,2] row_mask:0xf bank_mask:0xf bound_ctrl:1
	v_mov_b32_dpp v147, v181 quad_perm:[1,0,3,2] row_mask:0xf bank_mask:0xf bound_ctrl:1
	v_mov_b32_dpp v148, v182 quad_perm:[1,0,3,2] row_mask:0xf bank_mask:0xf bound_ctrl:1
	v_mov_b32_dpp v149, v183 quad_perm:[1,0,3,2] row_mask:0xf bank_mask:0xf bound_ctrl:1
	v_perm_b32 v157, v142, v176, v140
	v_perm_b32 v176, v142, v176, v141
	v_add_f32_e32 v112, v157, v112
	v_add_f32_e32 v113, v176, v113
	v_perm_b32 v157, v143, v177, v140
	v_perm_b32 v177, v143, v177, v141
	v_add_f32_e32 v114, v157, v114
	v_add_f32_e32 v115, v177, v115
	v_perm_b32 v157, v144, v178, v140
	v_perm_b32 v178, v144, v178, v141
	v_add_f32_e32 v116, v157, v116
	v_add_f32_e32 v117, v178, v117
	v_perm_b32 v157, v145, v179, v140
	v_perm_b32 v179, v145, v179, v141
	v_add_f32_e32 v118, v157, v118
	v_add_f32_e32 v119, v179, v119
	v_perm_b32 v157, v146, v180, v140
	v_perm_b32 v180, v146, v180, v141
	v_add_f32_e32 v124, v157, v124
	v_add_f32_e32 v125, v180, v125
	v_perm_b32 v157, v147, v181, v140
	v_perm_b32 v181, v147, v181, v141
	v_add_f32_e32 v126, v157, v126
	v_add_f32_e32 v127, v181, v127
	v_perm_b32 v157, v148, v182, v140
	v_perm_b32 v182, v148, v182, v141
	v_add_f32_e32 v120, v157, v120
	v_add_f32_e32 v121, v182, v121
	v_perm_b32 v157, v149, v183, v140
	v_perm_b32 v183, v149, v183, v141
	v_add_f32_e32 v122, v157, v122
	v_add_f32_e32 v123, v183, v123
	v_mul_f32_e32 v150, v112, v112
	v_mul_f32_e32 v151, v113, v113
	v_mul_f32_e32 v152, v114, v114
	v_mul_f32_e32 v153, v115, v115
	v_fmac_f32_e32 v150, v116, v116
	v_fmac_f32_e32 v151, v117, v117
	v_fmac_f32_e32 v152, v118, v118
	v_fmac_f32_e32 v153, v119, v119
	v_fmac_f32_e32 v150, v124, v124
	v_fmac_f32_e32 v151, v125, v125
	v_fmac_f32_e32 v152, v126, v126
	v_fmac_f32_e32 v153, v127, v127
	v_fmac_f32_e32 v150, v120, v120
	v_fmac_f32_e32 v151, v121, v121
	v_fmac_f32_e32 v152, v122, v122
	v_fmac_f32_e32 v153, v123, v123
	v_add_f32_dpp v150, v150, v150 row_ror:8 row_mask:0xf bank_mask:0xf bound_ctrl:1
	v_add_f32_dpp v151, v151, v151 row_ror:8 row_mask:0xf bank_mask:0xf bound_ctrl:1
	v_add_f32_dpp v152, v152, v152 row_ror:8 row_mask:0xf bank_mask:0xf bound_ctrl:1
	v_add_f32_dpp v153, v153, v153 row_ror:8 row_mask:0xf bank_mask:0xf bound_ctrl:1
	v_add_f32_dpp v150, v150, v150 row_ror:4 row_mask:0xf bank_mask:0xf bound_ctrl:1
	v_add_f32_dpp v151, v151, v151 row_ror:4 row_mask:0xf bank_mask:0xf bound_ctrl:1
	v_add_f32_dpp v152, v152, v152 row_ror:4 row_mask:0xf bank_mask:0xf bound_ctrl:1
	v_add_f32_dpp v153, v153, v153 row_ror:4 row_mask:0xf bank_mask:0xf bound_ctrl:1
	v_add_f32_dpp v150, v150, v150 row_ror:2 row_mask:0xf bank_mask:0xf bound_ctrl:1
	v_add_f32_dpp v151, v151, v151 row_ror:2 row_mask:0xf bank_mask:0xf bound_ctrl:1
	v_add_f32_dpp v152, v152, v152 row_ror:2 row_mask:0xf bank_mask:0xf bound_ctrl:1
	v_add_f32_dpp v153, v153, v153 row_ror:2 row_mask:0xf bank_mask:0xf bound_ctrl:1
	v_add_f32_dpp v150, v150, v150 row_ror:1 row_mask:0xf bank_mask:0xf bound_ctrl:1
	v_add_f32_dpp v151, v151, v151 row_ror:1 row_mask:0xf bank_mask:0xf bound_ctrl:1
	v_add_f32_dpp v152, v152, v152 row_ror:1 row_mask:0xf bank_mask:0xf bound_ctrl:1
	v_add_f32_dpp v153, v153, v153 row_ror:1 row_mask:0xf bank_mask:0xf bound_ctrl:1
	s_mov_b64 exec, s[0:1]
	ds_write_b32 v156, v150 offset:49152
	ds_write_b32 v156, v151 offset:49168
	ds_write_b32 v156, v152 offset:49184
	ds_write_b32 v156, v153 offset:49200
	s_mov_b64 exec, -1
	v_mov_b32_dpp v142, v184 quad_perm:[1,0,3,2] row_mask:0xf bank_mask:0xf bound_ctrl:1
	v_mov_b32_dpp v143, v185 quad_perm:[1,0,3,2] row_mask:0xf bank_mask:0xf bound_ctrl:1
	v_mov_b32_dpp v144, v186 quad_perm:[1,0,3,2] row_mask:0xf bank_mask:0xf bound_ctrl:1
	v_mov_b32_dpp v145, v187 quad_perm:[1,0,3,2] row_mask:0xf bank_mask:0xf bound_ctrl:1
	v_mov_b32_dpp v146, v188 quad_perm:[1,0,3,2] row_mask:0xf bank_mask:0xf bound_ctrl:1
	v_mov_b32_dpp v147, v189 quad_perm:[1,0,3,2] row_mask:0xf bank_mask:0xf bound_ctrl:1
	v_mov_b32_dpp v148, v190 quad_perm:[1,0,3,2] row_mask:0xf bank_mask:0xf bound_ctrl:1
	v_mov_b32_dpp v149, v191 quad_perm:[1,0,3,2] row_mask:0xf bank_mask:0xf bound_ctrl:1
	v_perm_b32 v157, v142, v184, v140
	v_perm_b32 v184, v142, v184, v141
	v_add_f32_e32 v96, v157, v96
	v_add_f32_e32 v97, v184, v97
	v_perm_b32 v157, v143, v185, v140
	v_perm_b32 v185, v143, v185, v141
	v_add_f32_e32 v98, v157, v98
	v_add_f32_e32 v99, v185, v99
	v_perm_b32 v157, v144, v186, v140
	v_perm_b32 v186, v144, v186, v141
	v_add_f32_e32 v100, v157, v100
	v_add_f32_e32 v101, v186, v101
	v_perm_b32 v157, v145, v187, v140
	v_perm_b32 v187, v145, v187, v141
	v_add_f32_e32 v102, v157, v102
	v_add_f32_e32 v103, v187, v103
	v_perm_b32 v157, v146, v188, v140
	v_perm_b32 v188, v146, v188, v141
	v_add_f32_e32 v108, v157, v108
	v_add_f32_e32 v109, v188, v109
	v_perm_b32 v157, v147, v189, v140
	v_perm_b32 v189, v147, v189, v141
	v_add_f32_e32 v110, v157, v110
	v_add_f32_e32 v111, v189, v111
	v_perm_b32 v157, v148, v190, v140
	v_perm_b32 v190, v148, v190, v141
	v_add_f32_e32 v104, v157, v104
	v_add_f32_e32 v105, v190, v105
	v_perm_b32 v157, v149, v191, v140
	v_perm_b32 v191, v149, v191, v141
	v_add_f32_e32 v106, v157, v106
	v_add_f32_e32 v107, v191, v107
	v_mul_f32_e32 v150, v96, v96
	v_mul_f32_e32 v151, v97, v97
	v_mul_f32_e32 v152, v98, v98
; __device__ __forceinline__ void load_rm4_bf16(const u16* base, size_t ld, int c, bool odd, float (&x)[4]) {
; #pragma unroll
;   for (int pr = 0; pr < 2; ++pr) {
;     unsigned w = *(const unsigned*)(base + (size_t)(2 * pr + (odd ? 1 : 0)) * ld + (c - (odd ? 1 : 0)));
;     float lo = __uint_as_float(w << 16), hi = __uint_as_float(w & 0xffff0000u);
;     float r = dpp_swap1(odd ? lo : hi);
;     x[2 * pr] = odd ? r : lo; x[2 * pr + 1] = odd ? hi : r;
;   }
; }
;   __device__ __forceinline__ void operator()(f32x4 (&acc)[2][2][4][2], int brow, int bcol, int wr, int wc, int fr, int fq) const {
;     ...
;     for (int ai = 0; ai < 2; ++ai)
; #pragma unroll
;       for (int m = 0; m < 4; ++m) {
;         int rl0 = ai * 128 + wr * 64 + m * 16 + fq * 4;
;         float sq[4] = {0.f, 0.f, 0.f, 0.f};
; #pragma unroll
;         for (int bj = 0; bj < 2; ++bj)
; #pragma unroll
;           for (int n = 0; n < 2; ++n) {
;             int c = bcol + bj * 128 + wc * 32 + n * 16 + fr;
;             float xv[4];
;             load_rm4_bf16(x1b + (size_t)(brow + rl0) * 1024, 1024, c, fr & 1, xv);
; #pragma unroll
;             for (int j = 0; j < 4; ++j) {
;               float v = xv[j] + acc[ai][bj][m][n][j];
;               acc[ai][bj][m][n][j] = v;
;               sq[j] += v * v;
;             }
;           }
; #pragma unroll
;         for (int j = 0; j < 4; ++j) {
;           float s = sq[j];
;           s = row16_sum(s);
;           if (fr == 0) part[(rl0 + j) * 4 + wc] = s;
;         }
;         __builtin_amdgcn_sched_barrier(0);
;       }
	v_mul_f32_e32 v153, v99, v99
	v_fmac_f32_e32 v150, v100, v100
	v_fmac_f32_e32 v151, v101, v101
	v_fmac_f32_e32 v152, v102, v102
	v_fmac_f32_e32 v153, v103, v103
	v_fmac_f32_e32 v150, v108, v108
	v_fmac_f32_e32 v151, v109, v109
	v_fmac_f32_e32 v152, v110, v110
	v_fmac_f32_e32 v153, v111, v111
	v_fmac_f32_e32 v150, v104, v104
	v_fmac_f32_e32 v151, v105, v105
	v_fmac_f32_e32 v152, v106, v106
	v_fmac_f32_e32 v153, v107, v107
	v_add_f32_dpp v150, v150, v150 row_ror:8 row_mask:0xf bank_mask:0xf bound_ctrl:1
	v_add_f32_dpp v151, v151, v151 row_ror:8 row_mask:0xf bank_mask:0xf bound_ctrl:1
	v_add_f32_dpp v152, v152, v152 row_ror:8 row_mask:0xf bank_mask:0xf bound_ctrl:1
	v_add_f32_dpp v153, v153, v153 row_ror:8 row_mask:0xf bank_mask:0xf bound_ctrl:1
	v_add_f32_dpp v150, v150, v150 row_ror:4 row_mask:0xf bank_mask:0xf bound_ctrl:1
	v_add_f32_dpp v151, v151, v151 row_ror:4 row_mask:0xf bank_mask:0xf bound_ctrl:1
	v_add_f32_dpp v152, v152, v152 row_ror:4 row_mask:0xf bank_mask:0xf bound_ctrl:1
	v_add_f32_dpp v153, v153, v153 row_ror:4 row_mask:0xf bank_mask:0xf bound_ctrl:1
	v_add_f32_dpp v150, v150, v150 row_ror:2 row_mask:0xf bank_mask:0xf bound_ctrl:1
	v_add_f32_dpp v151, v151, v151 row_ror:2 row_mask:0xf bank_mask:0xf bound_ctrl:1
	v_add_f32_dpp v152, v152, v152 row_ror:2 row_mask:0xf bank_mask:0xf bound_ctrl:1
	v_add_f32_dpp v153, v153, v153 row_ror:2 row_mask:0xf bank_mask:0xf bound_ctrl:1
	v_add_f32_dpp v150, v150, v150 row_ror:1 row_mask:0xf bank_mask:0xf bound_ctrl:1
	v_add_f32_dpp v151, v151, v151 row_ror:1 row_mask:0xf bank_mask:0xf bound_ctrl:1
	v_add_f32_dpp v152, v152, v152 row_ror:1 row_mask:0xf bank_mask:0xf bound_ctrl:1
	v_add_f32_dpp v153, v153, v153 row_ror:1 row_mask:0xf bank_mask:0xf bound_ctrl:1
	s_mov_b64 exec, s[0:1]
	ds_write_b32 v156, v150 offset:49408
	ds_write_b32 v156, v151 offset:49424
	ds_write_b32 v156, v152 offset:49440
	ds_write_b32 v156, v153 offset:49456
	s_mov_b64 exec, -1
	v_mov_b32_dpp v142, v192 quad_perm:[1,0,3,2] row_mask:0xf bank_mask:0xf bound_ctrl:1
	v_mov_b32_dpp v143, v193 quad_perm:[1,0,3,2] row_mask:0xf bank_mask:0xf bound_ctrl:1
	v_mov_b32_dpp v144, v194 quad_perm:[1,0,3,2] row_mask:0xf bank_mask:0xf bound_ctrl:1
	v_mov_b32_dpp v145, v195 quad_perm:[1,0,3,2] row_mask:0xf bank_mask:0xf bound_ctrl:1
	v_mov_b32_dpp v146, v196 quad_perm:[1,0,3,2] row_mask:0xf bank_mask:0xf bound_ctrl:1
	v_mov_b32_dpp v147, v197 quad_perm:[1,0,3,2] row_mask:0xf bank_mask:0xf bound_ctrl:1
	v_mov_b32_dpp v148, v198 quad_perm:[1,0,3,2] row_mask:0xf bank_mask:0xf bound_ctrl:1
	v_mov_b32_dpp v149, v199 quad_perm:[1,0,3,2] row_mask:0xf bank_mask:0xf bound_ctrl:1
	v_perm_b32 v157, v142, v192, v140
	v_perm_b32 v192, v142, v192, v141
	v_add_f32_e32 v80, v157, v80
	v_add_f32_e32 v81, v192, v81
	v_perm_b32 v157, v143, v193, v140
	v_perm_b32 v193, v143, v193, v141
	v_add_f32_e32 v82, v157, v82
	v_add_f32_e32 v83, v193, v83
	v_perm_b32 v157, v144, v194, v140
	v_perm_b32 v194, v144, v194, v141
	v_add_f32_e32 v84, v157, v84
	v_add_f32_e32 v85, v194, v85
	v_perm_b32 v157, v145, v195, v140
	v_perm_b32 v195, v145, v195, v141
	v_add_f32_e32 v86, v157, v86
	v_add_f32_e32 v87, v195, v87
	v_perm_b32 v157, v146, v196, v140
	v_perm_b32 v196, v146, v196, v141
	v_add_f32_e32 v92, v157, v92
	v_add_f32_e32 v93, v196, v93
	v_perm_b32 v157, v147, v197, v140
	v_perm_b32 v197, v147, v197, v141
	v_add_f32_e32 v94, v157, v94
	v_add_f32_e32 v95, v197, v95
	v_perm_b32 v157, v148, v198, v140
	v_perm_b32 v198, v148, v198, v141
	v_add_f32_e32 v88, v157, v88
	v_add_f32_e32 v89, v198, v89
	v_perm_b32 v157, v149, v199, v140
	v_perm_b32 v199, v149, v199, v141
	v_add_f32_e32 v90, v157, v90
	v_add_f32_e32 v91, v199, v91
	v_mul_f32_e32 v150, v80, v80
	v_mul_f32_e32 v151, v81, v81
	v_mul_f32_e32 v152, v82, v82
	v_mul_f32_e32 v153, v83, v83
	v_fmac_f32_e32 v150, v84, v84
	v_fmac_f32_e32 v151, v85, v85
	v_fmac_f32_e32 v152, v86, v86
	v_fmac_f32_e32 v153, v87, v87
	v_fmac_f32_e32 v150, v92, v92
	v_fmac_f32_e32 v151, v93, v93
	v_fmac_f32_e32 v152, v94, v94
	v_fmac_f32_e32 v153, v95, v95
	v_fmac_f32_e32 v150, v88, v88
	v_fmac_f32_e32 v151, v89, v89
	v_fmac_f32_e32 v152, v90, v90
	v_fmac_f32_e32 v153, v91, v91
	v_add_f32_dpp v150, v150, v150 row_ror:8 row_mask:0xf bank_mask:0xf bound_ctrl:1
	v_add_f32_dpp v151, v151, v151 row_ror:8 row_mask:0xf bank_mask:0xf bound_ctrl:1
	v_add_f32_dpp v152, v152, v152 row_ror:8 row_mask:0xf bank_mask:0xf bound_ctrl:1
	v_add_f32_dpp v153, v153, v153 row_ror:8 row_mask:0xf bank_mask:0xf bound_ctrl:1
	v_add_f32_dpp v150, v150, v150 row_ror:4 row_mask:0xf bank_mask:0xf bound_ctrl:1
	v_add_f32_dpp v151, v151, v151 row_ror:4 row_mask:0xf bank_mask:0xf bound_ctrl:1
	v_add_f32_dpp v152, v152, v152 row_ror:4 row_mask:0xf bank_mask:0xf bound_ctrl:1
	v_add_f32_dpp v153, v153, v153 row_ror:4 row_mask:0xf bank_mask:0xf bound_ctrl:1
	v_add_f32_dpp v150, v150, v150 row_ror:2 row_mask:0xf bank_mask:0xf bound_ctrl:1
	v_add_f32_dpp v151, v151, v151 row_ror:2 row_mask:0xf bank_mask:0xf bound_ctrl:1
	v_add_f32_dpp v152, v152, v152 row_ror:2 row_mask:0xf bank_mask:0xf bound_ctrl:1
	v_add_f32_dpp v153, v153, v153 row_ror:2 row_mask:0xf bank_mask:0xf bound_ctrl:1
	v_add_f32_dpp v150, v150, v150 row_ror:1 row_mask:0xf bank_mask:0xf bound_ctrl:1
	v_add_f32_dpp v151, v151, v151 row_ror:1 row_mask:0xf bank_mask:0xf bound_ctrl:1
	v_add_f32_dpp v152, v152, v152 row_ror:1 row_mask:0xf bank_mask:0xf bound_ctrl:1
	v_add_f32_dpp v153, v153, v153 row_ror:1 row_mask:0xf bank_mask:0xf bound_ctrl:1
	s_mov_b64 exec, s[0:1]
	ds_write_b32 v156, v150 offset:49664
	ds_write_b32 v156, v151 offset:49680
	ds_write_b32 v156, v152 offset:49696
	ds_write_b32 v156, v153 offset:49712
; __device__ __forceinline__ void load_rm4_bf16(const u16* base, size_t ld, int c, bool odd, float (&x)[4]) {
; #pragma unroll
;   for (int pr = 0; pr < 2; ++pr) {
;     unsigned w = *(const unsigned*)(base + (size_t)(2 * pr + (odd ? 1 : 0)) * ld + (c - (odd ? 1 : 0)));
;     float lo = __uint_as_float(w << 16), hi = __uint_as_float(w & 0xffff0000u);
;     float r = dpp_swap1(odd ? lo : hi);
;     x[2 * pr] = odd ? r : lo; x[2 * pr + 1] = odd ? hi : r;
;   }
; }
;   __device__ __forceinline__ void operator()(f32x4 (&acc)[2][2][4][2], int brow, int bcol, int wr, int wc, int fr, int fq) const {
;     ...
;     for (int ai = 0; ai < 2; ++ai)
; #pragma unroll
;       for (int m = 0; m < 4; ++m) {
;         int rl0 = ai * 128 + wr * 64 + m * 16 + fq * 4;
;         float sq[4] = {0.f, 0.f, 0.f, 0.f};
; #pragma unroll
;         for (int bj = 0; bj < 2; ++bj)
; #pragma unroll
;           for (int n = 0; n < 2; ++n) {
;             int c = bcol + bj * 128 + wc * 32 + n * 16 + fr;
;             float xv[4];
;             load_rm4_bf16(x1b + (size_t)(brow + rl0) * 1024, 1024, c, fr & 1, xv);
; #pragma unroll
;             for (int j = 0; j < 4; ++j) {
;               float v = xv[j] + acc[ai][bj][m][n][j];
;               acc[ai][bj][m][n][j] = v;
;               sq[j] += v * v;
;             }
;           }
; #pragma unroll
;         for (int j = 0; j < 4; ++j) {
;           float s = sq[j];
;           s = row16_sum(s);
;           if (fr == 0) part[(rl0 + j) * 4 + wc] = s;
;         }
;         __builtin_amdgcn_sched_barrier(0);
;       }
	s_mov_b64 exec, -1
	v_mov_b32_dpp v142, v200 quad_perm:[1,0,3,2] row_mask:0xf bank_mask:0xf bound_ctrl:1
	v_mov_b32_dpp v143, v201 quad_perm:[1,0,3,2] row_mask:0xf bank_mask:0xf bound_ctrl:1
	v_mov_b32_dpp v144, v202 quad_perm:[1,0,3,2] row_mask:0xf bank_mask:0xf bound_ctrl:1
	v_mov_b32_dpp v145, v203 quad_perm:[1,0,3,2] row_mask:0xf bank_mask:0xf bound_ctrl:1
	v_mov_b32_dpp v146, v204 quad_perm:[1,0,3,2] row_mask:0xf bank_mask:0xf bound_ctrl:1
	v_mov_b32_dpp v147, v205 quad_perm:[1,0,3,2] row_mask:0xf bank_mask:0xf bound_ctrl:1
	v_mov_b32_dpp v148, v206 quad_perm:[1,0,3,2] row_mask:0xf bank_mask:0xf bound_ctrl:1
	v_mov_b32_dpp v149, v207 quad_perm:[1,0,3,2] row_mask:0xf bank_mask:0xf bound_ctrl:1
	v_perm_b32 v157, v142, v200, v140
	v_perm_b32 v200, v142, v200, v141
	v_add_f32_e32 v64, v157, v64
	v_add_f32_e32 v65, v200, v65
	v_perm_b32 v157, v143, v201, v140
	v_perm_b32 v201, v143, v201, v141
	v_add_f32_e32 v66, v157, v66
	v_add_f32_e32 v67, v201, v67
	v_perm_b32 v157, v144, v202, v140
	v_perm_b32 v202, v144, v202, v141
	v_add_f32_e32 v68, v157, v68
	v_add_f32_e32 v69, v202, v69
	v_perm_b32 v157, v145, v203, v140
	v_perm_b32 v203, v145, v203, v141
	v_add_f32_e32 v70, v157, v70
	v_add_f32_e32 v71, v203, v71
	v_perm_b32 v157, v146, v204, v140
	v_perm_b32 v204, v146, v204, v141
	v_add_f32_e32 v76, v157, v76
	v_add_f32_e32 v77, v204, v77
	v_perm_b32 v157, v147, v205, v140
	v_perm_b32 v205, v147, v205, v141
	v_add_f32_e32 v78, v157, v78
	v_add_f32_e32 v79, v205, v79
	v_perm_b32 v157, v148, v206, v140
	v_perm_b32 v206, v148, v206, v141
	v_add_f32_e32 v72, v157, v72
	v_add_f32_e32 v73, v206, v73
	v_perm_b32 v157, v149, v207, v140
	v_perm_b32 v207, v149, v207, v141
	v_add_f32_e32 v74, v157, v74
	v_add_f32_e32 v75, v207, v75
	v_mul_f32_e32 v150, v64, v64
	v_mul_f32_e32 v151, v65, v65
	v_mul_f32_e32 v152, v66, v66
	v_mul_f32_e32 v153, v67, v67
	v_fmac_f32_e32 v150, v68, v68
	v_fmac_f32_e32 v151, v69, v69
	v_fmac_f32_e32 v152, v70, v70
	v_fmac_f32_e32 v153, v71, v71
	v_fmac_f32_e32 v150, v76, v76
	v_fmac_f32_e32 v151, v77, v77
	v_fmac_f32_e32 v152, v78, v78
	v_fmac_f32_e32 v153, v79, v79
	v_fmac_f32_e32 v150, v72, v72
	v_fmac_f32_e32 v151, v73, v73
	v_fmac_f32_e32 v152, v74, v74
	v_fmac_f32_e32 v153, v75, v75
	v_add_f32_dpp v150, v150, v150 row_ror:8 row_mask:0xf bank_mask:0xf bound_ctrl:1
	v_add_f32_dpp v151, v151, v151 row_ror:8 row_mask:0xf bank_mask:0xf bound_ctrl:1
	v_add_f32_dpp v152, v152, v152 row_ror:8 row_mask:0xf bank_mask:0xf bound_ctrl:1
	v_add_f32_dpp v153, v153, v153 row_ror:8 row_mask:0xf bank_mask:0xf bound_ctrl:1
	v_add_f32_dpp v150, v150, v150 row_ror:4 row_mask:0xf bank_mask:0xf bound_ctrl:1
	v_add_f32_dpp v151, v151, v151 row_ror:4 row_mask:0xf bank_mask:0xf bound_ctrl:1
	v_add_f32_dpp v152, v152, v152 row_ror:4 row_mask:0xf bank_mask:0xf bound_ctrl:1
	v_add_f32_dpp v153, v153, v153 row_ror:4 row_mask:0xf bank_mask:0xf bound_ctrl:1
	v_add_f32_dpp v150, v150, v150 row_ror:2 row_mask:0xf bank_mask:0xf bound_ctrl:1
	v_add_f32_dpp v151, v151, v151 row_ror:2 row_mask:0xf bank_mask:0xf bound_ctrl:1
	v_add_f32_dpp v152, v152, v152 row_ror:2 row_mask:0xf bank_mask:0xf bound_ctrl:1
	v_add_f32_dpp v153, v153, v153 row_ror:2 row_mask:0xf bank_mask:0xf bound_ctrl:1
	v_add_f32_dpp v150, v150, v150 row_ror:1 row_mask:0xf bank_mask:0xf bound_ctrl:1
	v_add_f32_dpp v151, v151, v151 row_ror:1 row_mask:0xf bank_mask:0xf bound_ctrl:1
	v_add_f32_dpp v152, v152, v152 row_ror:1 row_mask:0xf bank_mask:0xf bound_ctrl:1
	v_add_f32_dpp v153, v153, v153 row_ror:1 row_mask:0xf bank_mask:0xf bound_ctrl:1
	s_mov_b64 exec, s[0:1]
	ds_write_b32 v156, v150 offset:49920
	ds_write_b32 v156, v151 offset:49936
	ds_write_b32 v156, v152 offset:49952
	ds_write_b32 v156, v153 offset:49968
	s_mov_b64 exec, -1
	v_mov_b32_dpp v142, v208 quad_perm:[1,0,3,2] row_mask:0xf bank_mask:0xf bound_ctrl:1
	v_mov_b32_dpp v143, v209 quad_perm:[1,0,3,2] row_mask:0xf bank_mask:0xf bound_ctrl:1
	v_mov_b32_dpp v144, v210 quad_perm:[1,0,3,2] row_mask:0xf bank_mask:0xf bound_ctrl:1
	v_mov_b32_dpp v145, v211 quad_perm:[1,0,3,2] row_mask:0xf bank_mask:0xf bound_ctrl:1
	v_mov_b32_dpp v146, v212 quad_perm:[1,0,3,2] row_mask:0xf bank_mask:0xf bound_ctrl:1
	v_mov_b32_dpp v147, v213 quad_perm:[1,0,3,2] row_mask:0xf bank_mask:0xf bound_ctrl:1
	v_mov_b32_dpp v148, v214 quad_perm:[1,0,3,2] row_mask:0xf bank_mask:0xf bound_ctrl:1
	v_mov_b32_dpp v149, v215 quad_perm:[1,0,3,2] row_mask:0xf bank_mask:0xf bound_ctrl:1
	v_perm_b32 v157, v142, v208, v140
	v_perm_b32 v208, v142, v208, v141
	v_add_f32_e32 v48, v157, v48
	v_add_f32_e32 v49, v208, v49
	v_perm_b32 v157, v143, v209, v140
	v_perm_b32 v209, v143, v209, v141
	v_add_f32_e32 v50, v157, v50
	v_add_f32_e32 v51, v209, v51
	v_perm_b32 v157, v144, v210, v140
	v_perm_b32 v210, v144, v210, v141
	v_add_f32_e32 v52, v157, v52
	v_add_f32_e32 v53, v210, v53
	v_perm_b32 v157, v145, v211, v140
	v_perm_b32 v211, v145, v211, v141
	v_add_f32_e32 v54, v157, v54
	v_add_f32_e32 v55, v211, v55
	v_perm_b32 v157, v146, v212, v140
	v_perm_b32 v212, v146, v212, v141
	v_add_f32_e32 v60, v157, v60
	v_add_f32_e32 v61, v212, v61
	v_perm_b32 v157, v147, v213, v140
	v_perm_b32 v213, v147, v213, v141
	v_add_f32_e32 v62, v157, v62
	v_add_f32_e32 v63, v213, v63
	v_perm_b32 v157, v148, v214, v140
	v_perm_b32 v214, v148, v214, v141
	v_add_f32_e32 v56, v157, v56
	v_add_f32_e32 v57, v214, v57
	v_perm_b32 v157, v149, v215, v140
	v_perm_b32 v215, v149, v215, v141
	v_add_f32_e32 v58, v157, v58
	v_add_f32_e32 v59, v215, v59
	v_mul_f32_e32 v150, v48, v48
	v_mul_f32_e32 v151, v49, v49
	v_mul_f32_e32 v152, v50, v50
	v_mul_f32_e32 v153, v51, v51
	v_fmac_f32_e32 v150, v52, v52
; __device__ __forceinline__ void load_rm4_bf16(const u16* base, size_t ld, int c, bool odd, float (&x)[4]) {
; #pragma unroll
;   for (int pr = 0; pr < 2; ++pr) {
;     unsigned w = *(const unsigned*)(base + (size_t)(2 * pr + (odd ? 1 : 0)) * ld + (c - (odd ? 1 : 0)));
;     float lo = __uint_as_float(w << 16), hi = __uint_as_float(w & 0xffff0000u);
;     float r = dpp_swap1(odd ? lo : hi);
;     x[2 * pr] = odd ? r : lo; x[2 * pr + 1] = odd ? hi : r;
;   }
; }
;   __device__ __forceinline__ void operator()(f32x4 (&acc)[2][2][4][2], int brow, int bcol, int wr, int wc, int fr, int fq) const {
;     ...
;     for (int ai = 0; ai < 2; ++ai)
; #pragma unroll
;       for (int m = 0; m < 4; ++m) {
;         int rl0 = ai * 128 + wr * 64 + m * 16 + fq * 4;
;         float sq[4] = {0.f, 0.f, 0.f, 0.f};
; #pragma unroll
;         for (int bj = 0; bj < 2; ++bj)
; #pragma unroll
;           for (int n = 0; n < 2; ++n) {
;             int c = bcol + bj * 128 + wc * 32 + n * 16 + fr;
;             float xv[4];
;             load_rm4_bf16(x1b + (size_t)(brow + rl0) * 1024, 1024, c, fr & 1, xv);
; #pragma unroll
;             for (int j = 0; j < 4; ++j) {
;               float v = xv[j] + acc[ai][bj][m][n][j];
;               acc[ai][bj][m][n][j] = v;
;               sq[j] += v * v;
;             }
;           }
; #pragma unroll
;         for (int j = 0; j < 4; ++j) {
;           float s = sq[j];
;           s = row16_sum(s);
;           if (fr == 0) part[(rl0 + j) * 4 + wc] = s;
;         }
;         __builtin_amdgcn_sched_barrier(0);
;       }
	v_fmac_f32_e32 v151, v53, v53
	v_fmac_f32_e32 v152, v54, v54
	v_fmac_f32_e32 v153, v55, v55
	v_fmac_f32_e32 v150, v60, v60
	v_fmac_f32_e32 v151, v61, v61
	v_fmac_f32_e32 v152, v62, v62
	v_fmac_f32_e32 v153, v63, v63
	v_fmac_f32_e32 v150, v56, v56
	v_fmac_f32_e32 v151, v57, v57
	v_fmac_f32_e32 v152, v58, v58
	v_fmac_f32_e32 v153, v59, v59
	v_add_f32_dpp v150, v150, v150 row_ror:8 row_mask:0xf bank_mask:0xf bound_ctrl:1
	v_add_f32_dpp v151, v151, v151 row_ror:8 row_mask:0xf bank_mask:0xf bound_ctrl:1
	v_add_f32_dpp v152, v152, v152 row_ror:8 row_mask:0xf bank_mask:0xf bound_ctrl:1
	v_add_f32_dpp v153, v153, v153 row_ror:8 row_mask:0xf bank_mask:0xf bound_ctrl:1
	v_add_f32_dpp v150, v150, v150 row_ror:4 row_mask:0xf bank_mask:0xf bound_ctrl:1
	v_add_f32_dpp v151, v151, v151 row_ror:4 row_mask:0xf bank_mask:0xf bound_ctrl:1
	v_add_f32_dpp v152, v152, v152 row_ror:4 row_mask:0xf bank_mask:0xf bound_ctrl:1
	v_add_f32_dpp v153, v153, v153 row_ror:4 row_mask:0xf bank_mask:0xf bound_ctrl:1
	v_add_f32_dpp v150, v150, v150 row_ror:2 row_mask:0xf bank_mask:0xf bound_ctrl:1
	v_add_f32_dpp v151, v151, v151 row_ror:2 row_mask:0xf bank_mask:0xf bound_ctrl:1
	v_add_f32_dpp v152, v152, v152 row_ror:2 row_mask:0xf bank_mask:0xf bound_ctrl:1
	v_add_f32_dpp v153, v153, v153 row_ror:2 row_mask:0xf bank_mask:0xf bound_ctrl:1
	v_add_f32_dpp v150, v150, v150 row_ror:1 row_mask:0xf bank_mask:0xf bound_ctrl:1
	v_add_f32_dpp v151, v151, v151 row_ror:1 row_mask:0xf bank_mask:0xf bound_ctrl:1
	v_add_f32_dpp v152, v152, v152 row_ror:1 row_mask:0xf bank_mask:0xf bound_ctrl:1
	v_add_f32_dpp v153, v153, v153 row_ror:1 row_mask:0xf bank_mask:0xf bound_ctrl:1
	s_mov_b64 exec, s[0:1]
	ds_write_b32 v156, v150 offset:51200
	ds_write_b32 v156, v151 offset:51216
	ds_write_b32 v156, v152 offset:51232
	ds_write_b32 v156, v153 offset:51248
	s_mov_b64 exec, -1
	v_mov_b32_dpp v142, v216 quad_perm:[1,0,3,2] row_mask:0xf bank_mask:0xf bound_ctrl:1
	v_mov_b32_dpp v143, v217 quad_perm:[1,0,3,2] row_mask:0xf bank_mask:0xf bound_ctrl:1
	v_mov_b32_dpp v144, v218 quad_perm:[1,0,3,2] row_mask:0xf bank_mask:0xf bound_ctrl:1
	v_mov_b32_dpp v145, v219 quad_perm:[1,0,3,2] row_mask:0xf bank_mask:0xf bound_ctrl:1
	v_mov_b32_dpp v146, v220 quad_perm:[1,0,3,2] row_mask:0xf bank_mask:0xf bound_ctrl:1
	v_mov_b32_dpp v147, v221 quad_perm:[1,0,3,2] row_mask:0xf bank_mask:0xf bound_ctrl:1
	v_mov_b32_dpp v148, v222 quad_perm:[1,0,3,2] row_mask:0xf bank_mask:0xf bound_ctrl:1
	v_mov_b32_dpp v149, v223 quad_perm:[1,0,3,2] row_mask:0xf bank_mask:0xf bound_ctrl:1
	v_perm_b32 v157, v142, v216, v140
	v_perm_b32 v216, v142, v216, v141
	v_add_f32_e32 v32, v157, v32
	v_add_f32_e32 v33, v216, v33
	v_perm_b32 v157, v143, v217, v140
	v_perm_b32 v217, v143, v217, v141
	v_add_f32_e32 v34, v157, v34
	v_add_f32_e32 v35, v217, v35
	v_perm_b32 v157, v144, v218, v140
	v_perm_b32 v218, v144, v218, v141
	v_add_f32_e32 v36, v157, v36
	v_add_f32_e32 v37, v218, v37
	v_perm_b32 v157, v145, v219, v140
	v_perm_b32 v219, v145, v219, v141
	v_add_f32_e32 v38, v157, v38
	v_add_f32_e32 v39, v219, v39
	v_perm_b32 v157, v146, v220, v140
	v_perm_b32 v220, v146, v220, v141
	v_add_f32_e32 v44, v157, v44
	v_add_f32_e32 v45, v220, v45
	v_perm_b32 v157, v147, v221, v140
	v_perm_b32 v221, v147, v221, v141
	v_add_f32_e32 v46, v157, v46
	v_add_f32_e32 v47, v221, v47
	v_perm_b32 v157, v148, v222, v140
	v_perm_b32 v222, v148, v222, v141
	v_add_f32_e32 v40, v157, v40
	v_add_f32_e32 v41, v222, v41
	v_perm_b32 v157, v149, v223, v140
	v_perm_b32 v223, v149, v223, v141
	v_add_f32_e32 v42, v157, v42
	v_add_f32_e32 v43, v223, v43
	v_mul_f32_e32 v150, v32, v32
	v_mul_f32_e32 v151, v33, v33
	v_mul_f32_e32 v152, v34, v34
	v_mul_f32_e32 v153, v35, v35
	v_fmac_f32_e32 v150, v36, v36
	v_fmac_f32_e32 v151, v37, v37
	v_fmac_f32_e32 v152, v38, v38
	v_fmac_f32_e32 v153, v39, v39
	v_fmac_f32_e32 v150, v44, v44
	v_fmac_f32_e32 v151, v45, v45
	v_fmac_f32_e32 v152, v46, v46
	v_fmac_f32_e32 v153, v47, v47
	v_fmac_f32_e32 v150, v40, v40
	v_fmac_f32_e32 v151, v41, v41
	v_fmac_f32_e32 v152, v42, v42
	v_fmac_f32_e32 v153, v43, v43
	v_add_f32_dpp v150, v150, v150 row_ror:8 row_mask:0xf bank_mask:0xf bound_ctrl:1
	v_add_f32_dpp v151, v151, v151 row_ror:8 row_mask:0xf bank_mask:0xf bound_ctrl:1
	v_add_f32_dpp v152, v152, v152 row_ror:8 row_mask:0xf bank_mask:0xf bound_ctrl:1
	v_add_f32_dpp v153, v153, v153 row_ror:8 row_mask:0xf bank_mask:0xf bound_ctrl:1
	v_add_f32_dpp v150, v150, v150 row_ror:4 row_mask:0xf bank_mask:0xf bound_ctrl:1
	v_add_f32_dpp v151, v151, v151 row_ror:4 row_mask:0xf bank_mask:0xf bound_ctrl:1
	v_add_f32_dpp v152, v152, v152 row_ror:4 row_mask:0xf bank_mask:0xf bound_ctrl:1
	v_add_f32_dpp v153, v153, v153 row_ror:4 row_mask:0xf bank_mask:0xf bound_ctrl:1
	v_add_f32_dpp v150, v150, v150 row_ror:2 row_mask:0xf bank_mask:0xf bound_ctrl:1
	v_add_f32_dpp v151, v151, v151 row_ror:2 row_mask:0xf bank_mask:0xf bound_ctrl:1
	v_add_f32_dpp v152, v152, v152 row_ror:2 row_mask:0xf bank_mask:0xf bound_ctrl:1
	v_add_f32_dpp v153, v153, v153 row_ror:2 row_mask:0xf bank_mask:0xf bound_ctrl:1
	v_add_f32_dpp v150, v150, v150 row_ror:1 row_mask:0xf bank_mask:0xf bound_ctrl:1
	v_add_f32_dpp v151, v151, v151 row_ror:1 row_mask:0xf bank_mask:0xf bound_ctrl:1
	v_add_f32_dpp v152, v152, v152 row_ror:1 row_mask:0xf bank_mask:0xf bound_ctrl:1
	v_add_f32_dpp v153, v153, v153 row_ror:1 row_mask:0xf bank_mask:0xf bound_ctrl:1
	s_mov_b64 exec, s[0:1]
	ds_write_b32 v156, v150 offset:51456
	ds_write_b32 v156, v151 offset:51472
	ds_write_b32 v156, v152 offset:51488
	ds_write_b32 v156, v153 offset:51504
	s_mov_b64 exec, -1
	v_mov_b32_dpp v142, v224 quad_perm:[1,0,3,2] row_mask:0xf bank_mask:0xf bound_ctrl:1
; __device__ __forceinline__ void load_rm4_bf16(const u16* base, size_t ld, int c, bool odd, float (&x)[4]) {
; #pragma unroll
;   for (int pr = 0; pr < 2; ++pr) {
;     unsigned w = *(const unsigned*)(base + (size_t)(2 * pr + (odd ? 1 : 0)) * ld + (c - (odd ? 1 : 0)));
;     float lo = __uint_as_float(w << 16), hi = __uint_as_float(w & 0xffff0000u);
;     float r = dpp_swap1(odd ? lo : hi);
;     x[2 * pr] = odd ? r : lo; x[2 * pr + 1] = odd ? hi : r;
;   }
; }
;   __device__ __forceinline__ void operator()(f32x4 (&acc)[2][2][4][2], int brow, int bcol, int wr, int wc, int fr, int fq) const {
;     ...
;     for (int ai = 0; ai < 2; ++ai)
; #pragma unroll
;       for (int m = 0; m < 4; ++m) {
;         int rl0 = ai * 128 + wr * 64 + m * 16 + fq * 4;
;         float sq[4] = {0.f, 0.f, 0.f, 0.f};
; #pragma unroll
;         for (int bj = 0; bj < 2; ++bj)
; #pragma unroll
;           for (int n = 0; n < 2; ++n) {
;             int c = bcol + bj * 128 + wc * 32 + n * 16 + fr;
;             float xv[4];
;             load_rm4_bf16(x1b + (size_t)(brow + rl0) * 1024, 1024, c, fr & 1, xv);
; #pragma unroll
;             for (int j = 0; j < 4; ++j) {
;               float v = xv[j] + acc[ai][bj][m][n][j];
;               acc[ai][bj][m][n][j] = v;
;               sq[j] += v * v;
;             }
;           }
; #pragma unroll
;         for (int j = 0; j < 4; ++j) {
;           float s = sq[j];
;           s = row16_sum(s);
;           if (fr == 0) part[(rl0 + j) * 4 + wc] = s;
;         }
;         __builtin_amdgcn_sched_barrier(0);
;       }
	v_mov_b32_dpp v143, v225 quad_perm:[1,0,3,2] row_mask:0xf bank_mask:0xf bound_ctrl:1
	v_mov_b32_dpp v144, v226 quad_perm:[1,0,3,2] row_mask:0xf bank_mask:0xf bound_ctrl:1
	v_mov_b32_dpp v145, v227 quad_perm:[1,0,3,2] row_mask:0xf bank_mask:0xf bound_ctrl:1
	v_mov_b32_dpp v146, v228 quad_perm:[1,0,3,2] row_mask:0xf bank_mask:0xf bound_ctrl:1
	v_mov_b32_dpp v147, v229 quad_perm:[1,0,3,2] row_mask:0xf bank_mask:0xf bound_ctrl:1
	v_mov_b32_dpp v148, v230 quad_perm:[1,0,3,2] row_mask:0xf bank_mask:0xf bound_ctrl:1
	v_mov_b32_dpp v149, v231 quad_perm:[1,0,3,2] row_mask:0xf bank_mask:0xf bound_ctrl:1
	v_perm_b32 v157, v142, v224, v140
	v_perm_b32 v224, v142, v224, v141
	v_add_f32_e32 v16, v157, v16
	v_add_f32_e32 v17, v224, v17
	v_perm_b32 v157, v143, v225, v140
	v_perm_b32 v225, v143, v225, v141
	v_add_f32_e32 v18, v157, v18
	v_add_f32_e32 v19, v225, v19
	v_perm_b32 v157, v144, v226, v140
	v_perm_b32 v226, v144, v226, v141
	v_add_f32_e32 v20, v157, v20
	v_add_f32_e32 v21, v226, v21
	v_perm_b32 v157, v145, v227, v140
	v_perm_b32 v227, v145, v227, v141
	v_add_f32_e32 v22, v157, v22
	v_add_f32_e32 v23, v227, v23
	v_perm_b32 v157, v146, v228, v140
	v_perm_b32 v228, v146, v228, v141
	v_add_f32_e32 v28, v157, v28
	v_add_f32_e32 v29, v228, v29
	v_perm_b32 v157, v147, v229, v140
	v_perm_b32 v229, v147, v229, v141
	v_add_f32_e32 v30, v157, v30
	v_add_f32_e32 v31, v229, v31
	v_perm_b32 v157, v148, v230, v140
	v_perm_b32 v230, v148, v230, v141
	v_add_f32_e32 v24, v157, v24
	v_add_f32_e32 v25, v230, v25
	v_perm_b32 v157, v149, v231, v140
	v_perm_b32 v231, v149, v231, v141
	v_add_f32_e32 v26, v157, v26
	v_add_f32_e32 v27, v231, v27
	v_mul_f32_e32 v150, v16, v16
	v_mul_f32_e32 v151, v17, v17
	v_mul_f32_e32 v152, v18, v18
	v_mul_f32_e32 v153, v19, v19
	v_fmac_f32_e32 v150, v20, v20
	v_fmac_f32_e32 v151, v21, v21
	v_fmac_f32_e32 v152, v22, v22
	v_fmac_f32_e32 v153, v23, v23
	v_fmac_f32_e32 v150, v28, v28
	v_fmac_f32_e32 v151, v29, v29
	v_fmac_f32_e32 v152, v30, v30
	v_fmac_f32_e32 v153, v31, v31
	v_fmac_f32_e32 v150, v24, v24
	v_fmac_f32_e32 v151, v25, v25
	v_fmac_f32_e32 v152, v26, v26
	v_fmac_f32_e32 v153, v27, v27
	v_add_f32_dpp v150, v150, v150 row_ror:8 row_mask:0xf bank_mask:0xf bound_ctrl:1
	v_add_f32_dpp v151, v151, v151 row_ror:8 row_mask:0xf bank_mask:0xf bound_ctrl:1
	v_add_f32_dpp v152, v152, v152 row_ror:8 row_mask:0xf bank_mask:0xf bound_ctrl:1
	v_add_f32_dpp v153, v153, v153 row_ror:8 row_mask:0xf bank_mask:0xf bound_ctrl:1
	v_add_f32_dpp v150, v150, v150 row_ror:4 row_mask:0xf bank_mask:0xf bound_ctrl:1
	v_add_f32_dpp v151, v151, v151 row_ror:4 row_mask:0xf bank_mask:0xf bound_ctrl:1
	v_add_f32_dpp v152, v152, v152 row_ror:4 row_mask:0xf bank_mask:0xf bound_ctrl:1
	v_add_f32_dpp v153, v153, v153 row_ror:4 row_mask:0xf bank_mask:0xf bound_ctrl:1
	v_add_f32_dpp v150, v150, v150 row_ror:2 row_mask:0xf bank_mask:0xf bound_ctrl:1
	v_add_f32_dpp v151, v151, v151 row_ror:2 row_mask:0xf bank_mask:0xf bound_ctrl:1
	v_add_f32_dpp v152, v152, v152 row_ror:2 row_mask:0xf bank_mask:0xf bound_ctrl:1
	v_add_f32_dpp v153, v153, v153 row_ror:2 row_mask:0xf bank_mask:0xf bound_ctrl:1
	v_add_f32_dpp v150, v150, v150 row_ror:1 row_mask:0xf bank_mask:0xf bound_ctrl:1
	v_add_f32_dpp v151, v151, v151 row_ror:1 row_mask:0xf bank_mask:0xf bound_ctrl:1
	v_add_f32_dpp v152, v152, v152 row_ror:1 row_mask:0xf bank_mask:0xf bound_ctrl:1
	v_add_f32_dpp v153, v153, v153 row_ror:1 row_mask:0xf bank_mask:0xf bound_ctrl:1
	s_mov_b64 exec, s[0:1]
	ds_write_b32 v156, v150 offset:51712
	ds_write_b32 v156, v151 offset:51728
	ds_write_b32 v156, v152 offset:51744
	ds_write_b32 v156, v153 offset:51760
	s_mov_b64 exec, -1
	v_mov_b32_dpp v142, v232 quad_perm:[1,0,3,2] row_mask:0xf bank_mask:0xf bound_ctrl:1
	v_mov_b32_dpp v143, v233 quad_perm:[1,0,3,2] row_mask:0xf bank_mask:0xf bound_ctrl:1
	v_mov_b32_dpp v144, v234 quad_perm:[1,0,3,2] row_mask:0xf bank_mask:0xf bound_ctrl:1
	v_mov_b32_dpp v145, v235 quad_perm:[1,0,3,2] row_mask:0xf bank_mask:0xf bound_ctrl:1
;   __device__ __forceinline__ void operator()(f32x4 (&acc)[2][2][4][2], int brow, int bcol, int wr, int wc, int fr, int fq) const {
;     ...
;     for (int ai = 0; ai < 2; ++ai)
; #pragma unroll
;       for (int m = 0; m < 4; ++m) {
;         int rl0 = ai * 128 + wr * 64 + m * 16 + fq * 4;
;         float sq[4] = {0.f, 0.f, 0.f, 0.f};
; #pragma unroll
;         for (int bj = 0; bj < 2; ++bj)
; #pragma unroll
;           for (int n = 0; n < 2; ++n) {
;             int c = bcol + bj * 128 + wc * 32 + n * 16 + fr;
;             float xv[4];
;             load_rm4_bf16(x1b + (size_t)(brow + rl0) * 1024, 1024, c, fr & 1, xv);
; #pragma unroll
;             for (int j = 0; j < 4; ++j) {
;               float v = xv[j] + acc[ai][bj][m][n][j];
;               acc[ai][bj][m][n][j] = v;
;               sq[j] += v * v;
;             }
;           }
; #pragma unroll
;         for (int j = 0; j < 4; ++j) {
;           float s = sq[j];
;           s = row16_sum(s);
;           if (fr == 0) part[(rl0 + j) * 4 + wc] = s;
;         }
;         __builtin_amdgcn_sched_barrier(0);
;       }
;     __syncthreads();
;     if (tid < 256) {
;       float s = part[tid * 4] + part[tid * 4 + 1] + part[tid * 4 + 2] + part[tid * 4 + 3];
;       unsigned long long g = (unsigned long long)__float_as_uint(s) | (1ull << 32);
;       __hip_atomic_store(gran + (size_t)(brow + tid) * 4 + ntile, g, __ATOMIC_RELAXED, __HIP_MEMORY_SCOPE_AGENT);
;     }
	v_mov_b32_dpp v146, v236 quad_perm:[1,0,3,2] row_mask:0xf bank_mask:0xf bound_ctrl:1
	v_mov_b32_dpp v147, v237 quad_perm:[1,0,3,2] row_mask:0xf bank_mask:0xf bound_ctrl:1
	v_mov_b32_dpp v148, v238 quad_perm:[1,0,3,2] row_mask:0xf bank_mask:0xf bound_ctrl:1
	v_mov_b32_dpp v149, v239 quad_perm:[1,0,3,2] row_mask:0xf bank_mask:0xf bound_ctrl:1
	v_perm_b32 v157, v142, v232, v140
	v_perm_b32 v232, v142, v232, v141
	v_add_f32_e32 v240, v157, v0
	v_add_f32_e32 v241, v232, v1
	v_perm_b32 v157, v143, v233, v140
	v_perm_b32 v233, v143, v233, v141
	v_add_f32_e32 v242, v157, v2
	v_add_f32_e32 v243, v233, v3
	v_perm_b32 v157, v144, v234, v140
	v_perm_b32 v234, v144, v234, v141
	v_add_f32_e32 v244, v157, v4
	v_add_f32_e32 v245, v234, v5
	v_perm_b32 v157, v145, v235, v140
	v_perm_b32 v235, v145, v235, v141
	v_add_f32_e32 v246, v157, v6
	v_add_f32_e32 v247, v235, v7
	v_perm_b32 v157, v146, v236, v140
	v_perm_b32 v236, v146, v236, v141
	v_add_f32_e32 v12, v157, v12
	v_add_f32_e32 v13, v236, v13
	v_perm_b32 v157, v147, v237, v140
	v_perm_b32 v237, v147, v237, v141
	v_add_f32_e32 v14, v157, v14
	v_add_f32_e32 v15, v237, v15
	v_perm_b32 v157, v148, v238, v140
	v_perm_b32 v238, v148, v238, v141
	v_add_f32_e32 v248, v157, v8
	v_add_f32_e32 v249, v238, v9
	v_perm_b32 v157, v149, v239, v140
	v_perm_b32 v239, v149, v239, v141
	v_add_f32_e32 v10, v157, v10
	v_add_f32_e32 v11, v239, v11
	v_mul_f32_e32 v150, v240, v240
	v_mul_f32_e32 v151, v241, v241
	v_mul_f32_e32 v152, v242, v242
	v_mul_f32_e32 v153, v243, v243
	v_fmac_f32_e32 v150, v244, v244
	v_fmac_f32_e32 v151, v245, v245
	v_fmac_f32_e32 v152, v246, v246
	v_fmac_f32_e32 v153, v247, v247
	v_fmac_f32_e32 v150, v12, v12
	v_fmac_f32_e32 v151, v13, v13
	v_fmac_f32_e32 v152, v14, v14
	v_fmac_f32_e32 v153, v15, v15
	v_fmac_f32_e32 v150, v248, v248
	v_fmac_f32_e32 v151, v249, v249
	v_fmac_f32_e32 v152, v10, v10
	v_fmac_f32_e32 v153, v11, v11
	v_add_f32_dpp v150, v150, v150 row_ror:8 row_mask:0xf bank_mask:0xf bound_ctrl:1
	v_add_f32_dpp v151, v151, v151 row_ror:8 row_mask:0xf bank_mask:0xf bound_ctrl:1
	v_add_f32_dpp v152, v152, v152 row_ror:8 row_mask:0xf bank_mask:0xf bound_ctrl:1
	v_add_f32_dpp v153, v153, v153 row_ror:8 row_mask:0xf bank_mask:0xf bound_ctrl:1
	v_add_f32_dpp v150, v150, v150 row_ror:4 row_mask:0xf bank_mask:0xf bound_ctrl:1
	v_add_f32_dpp v151, v151, v151 row_ror:4 row_mask:0xf bank_mask:0xf bound_ctrl:1
	v_add_f32_dpp v152, v152, v152 row_ror:4 row_mask:0xf bank_mask:0xf bound_ctrl:1
	v_add_f32_dpp v153, v153, v153 row_ror:4 row_mask:0xf bank_mask:0xf bound_ctrl:1
	v_add_f32_dpp v150, v150, v150 row_ror:2 row_mask:0xf bank_mask:0xf bound_ctrl:1
	v_add_f32_dpp v151, v151, v151 row_ror:2 row_mask:0xf bank_mask:0xf bound_ctrl:1
	v_add_f32_dpp v152, v152, v152 row_ror:2 row_mask:0xf bank_mask:0xf bound_ctrl:1
	v_add_f32_dpp v153, v153, v153 row_ror:2 row_mask:0xf bank_mask:0xf bound_ctrl:1
	v_add_f32_dpp v150, v150, v150 row_ror:1 row_mask:0xf bank_mask:0xf bound_ctrl:1
	v_add_f32_dpp v151, v151, v151 row_ror:1 row_mask:0xf bank_mask:0xf bound_ctrl:1
	v_add_f32_dpp v152, v152, v152 row_ror:1 row_mask:0xf bank_mask:0xf bound_ctrl:1
	v_add_f32_dpp v153, v153, v153 row_ror:1 row_mask:0xf bank_mask:0xf bound_ctrl:1
	s_mov_b64 exec, s[0:1]
	ds_write_b32 v156, v150 offset:51968
	ds_write_b32 v156, v151 offset:51984
	ds_write_b32 v156, v152 offset:52000
	ds_write_b32 v156, v153 offset:52016
	s_mov_b64 exec, -1
	v_add_u32_e32 v135, s33, v132
	v_add_u32_e32 v0, s58, v135
	v_cmp_gt_i32_e64 s[2:3], s42, v135
	v_ashrrev_i32_e32 v1, 31, v0
	s_waitcnt lgkmcnt(0)
	s_barrier
	s_and_saveexec_b64 s[18:19], s[2:3]
	s_cbranch_execz .LBB0_734
	v_lshl_add_u32 v2, v135, 4, 16
	ds_read_b128 v[2:5], v2 offset:49152
	s_ashr_i32 s20, s59, 8
	v_lshlrev_b64 v[6:7], 5, v[0:1]
	v_lshl_add_u64 v[6:7], s[38:39], 0, v[6:7]
	s_ashr_i32 s21, s20, 31
	s_waitcnt lgkmcnt(0)
	v_add_f32_e32 v2, v2, v3
	v_add_f32_e32 v2, v2, v4
	v_add_f32_e32 v130, v2, v5
	v_lshl_add_u64 v[2:3], s[20:21], 3, v[6:7]
	global_store_dwordx2 v[2:3], v[130:131], off sc1
